# in-projection epilogue: the 480 flat_store_short (generic-pointer stores of the transposed outputs) turned into global_store_short
# speedup vs baseline: 1.0133x; 1.0133x over previous
; #define STT(BASE, MUL) { bf16_t* q_ = (BASE) + (size_t)(4 * h) * TOK; _Pragma("unroll") for (int mi = 0; mi < 4; ++mi) _Pragma("unroll") for (int g = 0; g < 4; ++g) { \
;       _Pragma("unroll") for (int e = 0; e < 4; ++e) q_[(size_t)e * TOK] = f2bf(acc[mi][NI][4 * g + e] * (MUL)); q_ += (size_t)8 * TOK; asm volatile("" : "+v"(q_)); } }
; template <int NI> DI void inproj_epi_reg(const Params& p, int layer, int nt, int tok, int h, f32x16 (&acc)[4][2]) {
;     ...
;   } else {
;     bf16_t* VT = (bf16_t*)(p.ws + O_DVT) + (size_t)((nt - 40) * 128) * TOK + tok;
;     STT(VT, 1.f);
;   }
.LBB0_195:
	s_waitcnt vmcnt(1)
	v_mov_b32_e32 v131, v0
	s_nop 0
	v_ashrrev_i32_e32 v130, 8, v131
	v_lshl_add_u32 v237, s7, 1, v130
	v_and_b32_e32 v132, 0xdf, v131
	v_bfe_u32 v193, v131, 5, 1
	v_or_b32_e32 v130, s8, v132
	v_cmp_lt_i32_e64 s[42:43], 3, v237
	s_and_saveexec_b64 s[8:9], s[42:43]
	s_xor_b64 s[8:9], exec, s[8:9]
	s_cbranch_execz .LBB0_221
	v_cmp_lt_u32_e32 vcc, 7, v237
	s_and_saveexec_b64 s[10:11], vcc
	s_xor_b64 s[10:11], exec, s[10:11]
	s_cbranch_execz .LBB0_218
	v_add_u32_e32 v133, 0x1f00, v130
	v_bfe_u32 v138, v133, 6, 7
	v_and_b32_e32 v133, 31, v131
	v_cmp_lt_u32_e32 vcc, 15, v237
	s_and_saveexec_b64 s[12:13], vcc
	s_xor_b64 s[12:13], exec, s[12:13]
	s_cbranch_execz .LBB0_211
	v_cmp_lt_u32_e32 vcc, 19, v237
	s_and_saveexec_b64 s[14:15], vcc
	s_xor_b64 s[14:15], exec, s[14:15]
	s_cbranch_execz .LBB0_208
	v_cmp_lt_u32_e32 vcc, 23, v237
	s_and_saveexec_b64 s[16:17], vcc
	s_xor_b64 s[16:17], exec, s[16:17]
	s_cbranch_execz .LBB0_205
	v_cmp_lt_u32_e32 vcc, 39, v237
	s_and_saveexec_b64 s[18:19], vcc
	s_xor_b64 s[18:19], exec, s[18:19]
	s_cbranch_execz .LBB0_202
	v_readlane_b32 s44, v253, 54
	v_mov_b32_e32 v131, 0xffffec00
	v_readlane_b32 s45, v253, 55
	v_lshl_add_u32 v131, v237, 7, v131
	v_mov_b32_e32 v133, v181
	s_waitcnt vmcnt(0)
	v_mov_b64_e32 v[134:135], s[44:45]
	s_ashr_i32 s7, s6, 31
	v_mad_u64_u32 v[134:135], s[44:45], v131, s29, v[134:135]
	v_lshl_add_u64 v[136:137], v[132:133], 0, s[6:7]
	v_mul_u32_u24_e32 v131, 0x8400, v193
	v_lshl_add_u64 v[134:135], v[136:137], 1, v[134:135]
	v_lshlrev_b32_e32 v180, 1, v131
	v_lshl_add_u64 v[134:135], v[134:135], 0, v[180:181]
	v_cvt_pk_bf16_f32 v114, v114, s0
	global_store_short v[134:135], v114, off offset:512
	v_add_co_u32_e32 v114, vcc, s48, v134
	v_cvt_pk_bf16_f32 v131, v115, s0
	s_nop 0
	v_addc_co_u32_e32 v115, vcc, 0, v135, vcc
	s_mov_b32 s44, 0x8000
	global_store_short v[114:115], v131, off offset:1024
	v_add_co_u32_e32 v114, vcc, s44, v134
	v_cvt_pk_bf16_f32 v116, v116, s0
	s_nop 0
	v_addc_co_u32_e32 v115, vcc, 0, v135, vcc
	s_mov_b32 s7, 0xc000
	global_store_short v[114:115], v116, off offset:1536
	v_add_co_u32_e32 v114, vcc, s7, v134
	v_cvt_pk_bf16_f32 v116, v117, s0
	s_nop 0
	v_addc_co_u32_e32 v115, vcc, 0, v135, vcc
	s_mov_b64 s[52:53], 0x21200
	global_store_short v[114:115], v116, off offset:2048
	v_lshl_add_u64 v[114:115], v[134:135], 0, s[52:53]
	v_cvt_pk_bf16_f32 v116, v118, s0
	global_store_short v[114:115], v116, off
	v_add_co_u32_e32 v116, vcc, s48, v114
	v_cvt_pk_bf16_f32 v118, v119, s0
	s_nop 0
	v_addc_co_u32_e32 v117, vcc, 0, v115, vcc
	global_store_short v[116:117], v118, off offset:512
	v_add_co_u32_e32 v116, vcc, s44, v114
	v_cvt_pk_bf16_f32 v118, v120, s0
	s_nop 0
	v_addc_co_u32_e32 v117, vcc, 0, v115, vcc
	global_store_short v[116:117], v118, off offset:1024
	v_add_co_u32_e32 v116, vcc, s7, v114
	v_cvt_pk_bf16_f32 v118, v121, s0
	s_nop 0
	v_addc_co_u32_e32 v117, vcc, 0, v115, vcc
	s_mov_b64 s[52:53], 0x21000
	global_store_short v[116:117], v118, off offset:1536
	v_lshl_add_u64 v[114:115], v[114:115], 0, s[52:53]
	v_cvt_pk_bf16_f32 v116, v122, s0
	global_store_short v[114:115], v116, off
	v_add_co_u32_e32 v116, vcc, s48, v114
	v_cvt_pk_bf16_f32 v118, v123, s0
	s_nop 0
	v_addc_co_u32_e32 v117, vcc, 0, v115, vcc
	global_store_short v[116:117], v118, off offset:512
	v_add_co_u32_e32 v116, vcc, s44, v114
	v_cvt_pk_bf16_f32 v118, v124, s0
	s_nop 0
	v_addc_co_u32_e32 v117, vcc, 0, v115, vcc
	global_store_short v[116:117], v118, off offset:1024
	v_add_co_u32_e32 v116, vcc, s7, v114
	v_cvt_pk_bf16_f32 v118, v125, s0
	s_nop 0
	v_addc_co_u32_e32 v117, vcc, 0, v115, vcc
	global_store_short v[116:117], v118, off offset:1536
	v_lshl_add_u64 v[114:115], v[114:115], 0, s[52:53]
	v_cvt_pk_bf16_f32 v116, v126, s0
	global_store_short v[114:115], v116, off
	v_add_co_u32_e32 v116, vcc, s48, v114
	v_cvt_pk_bf16_f32 v118, v127, s0
	s_nop 0
	v_addc_co_u32_e32 v117, vcc, 0, v115, vcc
	global_store_short v[116:117], v118, off offset:512
	v_add_co_u32_e32 v116, vcc, s44, v114
	v_cvt_pk_bf16_f32 v118, v128, s0
	s_nop 0
	v_addc_co_u32_e32 v117, vcc, 0, v115, vcc
	global_store_short v[116:117], v118, off offset:1024
	v_add_co_u32_e32 v116, vcc, s7, v114
	v_cvt_pk_bf16_f32 v118, v129, s0
	s_nop 0
	v_addc_co_u32_e32 v117, vcc, 0, v115, vcc
	v_lshl_add_u64 v[114:115], v[114:115], 0, s[52:53]
	v_cvt_pk_bf16_f32 v98, v98, s0
	global_store_short v[116:117], v118, off offset:1536
	global_store_short v[114:115], v98, off
	v_add_co_u32_e32 v98, vcc, s48, v114
	v_cvt_pk_bf16_f32 v116, v99, s0
	s_nop 0
	v_addc_co_u32_e32 v99, vcc, 0, v115, vcc
	global_store_short v[98:99], v116, off offset:512
	v_add_co_u32_e32 v98, vcc, s44, v114
	v_cvt_pk_bf16_f32 v100, v100, s0
	s_nop 0
	v_addc_co_u32_e32 v99, vcc, 0, v115, vcc
	global_store_short v[98:99], v100, off offset:1024
	v_add_co_u32_e32 v98, vcc, s7, v114
	v_cvt_pk_bf16_f32 v100, v101, s0
	s_nop 0
	v_addc_co_u32_e32 v99, vcc, 0, v115, vcc
	global_store_short v[98:99], v100, off offset:1536
	v_lshl_add_u64 v[98:99], v[114:115], 0, s[52:53]
	v_cvt_pk_bf16_f32 v100, v102, s0
	global_store_short v[98:99], v100, off
	v_add_co_u32_e32 v100, vcc, s48, v98
	v_cvt_pk_bf16_f32 v102, v103, s0
	s_nop 0
	v_addc_co_u32_e32 v101, vcc, 0, v99, vcc
	global_store_short v[100:101], v102, off offset:512
	v_add_co_u32_e32 v100, vcc, s44, v98
	v_cvt_pk_bf16_f32 v102, v104, s0
	s_nop 0
	v_addc_co_u32_e32 v101, vcc, 0, v99, vcc
	global_store_short v[100:101], v102, off offset:1024
	v_add_co_u32_e32 v100, vcc, s7, v98
	v_cvt_pk_bf16_f32 v102, v105, s0
	s_nop 0
	v_addc_co_u32_e32 v101, vcc, 0, v99, vcc
	global_store_short v[100:101], v102, off offset:1536
; #define STT(BASE, MUL) { bf16_t* q_ = (BASE) + (size_t)(4 * h) * TOK; _Pragma("unroll") for (int mi = 0; mi < 4; ++mi) _Pragma("unroll") for (int g = 0; g < 4; ++g) { \
;       _Pragma("unroll") for (int e = 0; e < 4; ++e) q_[(size_t)e * TOK] = f2bf(acc[mi][NI][4 * g + e] * (MUL)); q_ += (size_t)8 * TOK; asm volatile("" : "+v"(q_)); } }
; template <int NI> DI void inproj_epi_reg(const Params& p, int layer, int nt, int tok, int h, f32x16 (&acc)[4][2]) {
;     ...
;   } else {
;     bf16_t* VT = (bf16_t*)(p.ws + O_DVT) + (size_t)((nt - 40) * 128) * TOK + tok;
;     STT(VT, 1.f);
;   }
	v_lshl_add_u64 v[98:99], v[98:99], 0, s[52:53]
	v_cvt_pk_bf16_f32 v100, v106, s0
	global_store_short v[98:99], v100, off
	v_add_co_u32_e32 v100, vcc, s48, v98
	v_cvt_pk_bf16_f32 v102, v107, s0
	s_nop 0
	v_addc_co_u32_e32 v101, vcc, 0, v99, vcc
	global_store_short v[100:101], v102, off offset:512
	v_add_co_u32_e32 v100, vcc, s44, v98
	v_cvt_pk_bf16_f32 v102, v108, s0
	s_nop 0
	v_addc_co_u32_e32 v101, vcc, 0, v99, vcc
	global_store_short v[100:101], v102, off offset:1024
	v_add_co_u32_e32 v100, vcc, s7, v98
	v_cvt_pk_bf16_f32 v102, v109, s0
	s_nop 0
	v_addc_co_u32_e32 v101, vcc, 0, v99, vcc
	global_store_short v[100:101], v102, off offset:1536
	v_lshl_add_u64 v[98:99], v[98:99], 0, s[52:53]
	v_cvt_pk_bf16_f32 v100, v110, s0
	global_store_short v[98:99], v100, off
	v_add_co_u32_e32 v100, vcc, s48, v98
	v_cvt_pk_bf16_f32 v102, v111, s0
	s_nop 0
	v_addc_co_u32_e32 v101, vcc, 0, v99, vcc
	global_store_short v[100:101], v102, off offset:512
	v_add_co_u32_e32 v100, vcc, s44, v98
	v_cvt_pk_bf16_f32 v102, v112, s0
	s_nop 0
	v_addc_co_u32_e32 v101, vcc, 0, v99, vcc
	global_store_short v[100:101], v102, off offset:1024
	v_add_co_u32_e32 v100, vcc, s7, v98
	v_cvt_pk_bf16_f32 v102, v113, s0
	s_nop 0
	v_addc_co_u32_e32 v101, vcc, 0, v99, vcc
	v_lshl_add_u64 v[98:99], v[98:99], 0, s[52:53]
	v_cvt_pk_bf16_f32 v82, v82, s0
	global_store_short v[100:101], v102, off offset:1536
	global_store_short v[98:99], v82, off
	v_add_co_u32_e32 v82, vcc, s48, v98
	v_cvt_pk_bf16_f32 v100, v83, s0
	s_nop 0
	v_addc_co_u32_e32 v83, vcc, 0, v99, vcc
	global_store_short v[82:83], v100, off offset:512
	v_add_co_u32_e32 v82, vcc, s44, v98
	v_cvt_pk_bf16_f32 v84, v84, s0
	s_nop 0
	v_addc_co_u32_e32 v83, vcc, 0, v99, vcc
	global_store_short v[82:83], v84, off offset:1024
	v_add_co_u32_e32 v82, vcc, s7, v98
	v_cvt_pk_bf16_f32 v84, v85, s0
	s_nop 0
	v_addc_co_u32_e32 v83, vcc, 0, v99, vcc
	global_store_short v[82:83], v84, off offset:1536
	v_lshl_add_u64 v[82:83], v[98:99], 0, s[52:53]
	v_cvt_pk_bf16_f32 v84, v86, s0
	global_store_short v[82:83], v84, off
	v_add_co_u32_e32 v84, vcc, s48, v82
	v_cvt_pk_bf16_f32 v86, v87, s0
	s_nop 0
	v_addc_co_u32_e32 v85, vcc, 0, v83, vcc
	global_store_short v[84:85], v86, off offset:512
	v_add_co_u32_e32 v84, vcc, s44, v82
	v_cvt_pk_bf16_f32 v86, v88, s0
	s_nop 0
	v_addc_co_u32_e32 v85, vcc, 0, v83, vcc
	global_store_short v[84:85], v86, off offset:1024
	v_add_co_u32_e32 v84, vcc, s7, v82
	v_cvt_pk_bf16_f32 v86, v89, s0
	s_nop 0
	v_addc_co_u32_e32 v85, vcc, 0, v83, vcc
	global_store_short v[84:85], v86, off offset:1536
	v_lshl_add_u64 v[82:83], v[82:83], 0, s[52:53]
	v_cvt_pk_bf16_f32 v84, v90, s0
	global_store_short v[82:83], v84, off
	v_add_co_u32_e32 v84, vcc, s48, v82
	v_cvt_pk_bf16_f32 v86, v91, s0
	s_nop 0
	v_addc_co_u32_e32 v85, vcc, 0, v83, vcc
	global_store_short v[84:85], v86, off offset:512
	v_add_co_u32_e32 v84, vcc, s44, v82
	v_cvt_pk_bf16_f32 v86, v92, s0
	s_nop 0
	v_addc_co_u32_e32 v85, vcc, 0, v83, vcc
	global_store_short v[84:85], v86, off offset:1024
	v_add_co_u32_e32 v84, vcc, s7, v82
	v_cvt_pk_bf16_f32 v86, v93, s0
	s_nop 0
	v_addc_co_u32_e32 v85, vcc, 0, v83, vcc
	global_store_short v[84:85], v86, off offset:1536
	v_lshl_add_u64 v[82:83], v[82:83], 0, s[52:53]
	v_cvt_pk_bf16_f32 v84, v94, s0
	global_store_short v[82:83], v84, off
	v_add_co_u32_e32 v84, vcc, s48, v82
	v_cvt_pk_bf16_f32 v86, v95, s0
	s_nop 0
	v_addc_co_u32_e32 v85, vcc, 0, v83, vcc
	global_store_short v[84:85], v86, off offset:512
	v_add_co_u32_e32 v84, vcc, s44, v82
	v_cvt_pk_bf16_f32 v86, v96, s0
	s_nop 0
	v_addc_co_u32_e32 v85, vcc, 0, v83, vcc
	global_store_short v[84:85], v86, off offset:1024
	v_add_co_u32_e32 v84, vcc, s7, v82
	v_cvt_pk_bf16_f32 v86, v97, s0
	s_nop 0
	v_addc_co_u32_e32 v85, vcc, 0, v83, vcc
	v_lshl_add_u64 v[82:83], v[82:83], 0, s[52:53]
	v_cvt_pk_bf16_f32 v66, v66, s0
	global_store_short v[84:85], v86, off offset:1536
	global_store_short v[82:83], v66, off
	v_add_co_u32_e32 v66, vcc, s48, v82
	v_cvt_pk_bf16_f32 v84, v67, s0
	s_nop 0
	v_addc_co_u32_e32 v67, vcc, 0, v83, vcc
	global_store_short v[66:67], v84, off offset:512
	v_add_co_u32_e32 v66, vcc, s44, v82
	v_cvt_pk_bf16_f32 v68, v68, s0
	s_nop 0
	v_addc_co_u32_e32 v67, vcc, 0, v83, vcc
	global_store_short v[66:67], v68, off offset:1024
	v_add_co_u32_e32 v66, vcc, s7, v82
	v_cvt_pk_bf16_f32 v68, v69, s0
	s_nop 0
	v_addc_co_u32_e32 v67, vcc, 0, v83, vcc
	global_store_short v[66:67], v68, off offset:1536
	v_lshl_add_u64 v[66:67], v[82:83], 0, s[52:53]
	v_cvt_pk_bf16_f32 v68, v70, s0
	global_store_short v[66:67], v68, off
	v_add_co_u32_e32 v68, vcc, s48, v66
	v_cvt_pk_bf16_f32 v70, v71, s0
	s_nop 0
	v_addc_co_u32_e32 v69, vcc, 0, v67, vcc
	global_store_short v[68:69], v70, off offset:512
	v_add_co_u32_e32 v68, vcc, s44, v66
	v_cvt_pk_bf16_f32 v70, v72, s0
	s_nop 0
	v_addc_co_u32_e32 v69, vcc, 0, v67, vcc
	global_store_short v[68:69], v70, off offset:1024
	v_add_co_u32_e32 v68, vcc, s7, v66
	v_cvt_pk_bf16_f32 v70, v73, s0
	s_nop 0
	v_addc_co_u32_e32 v69, vcc, 0, v67, vcc
	global_store_short v[68:69], v70, off offset:1536
	v_lshl_add_u64 v[66:67], v[66:67], 0, s[52:53]
	v_cvt_pk_bf16_f32 v68, v74, s0
	global_store_short v[66:67], v68, off
	v_add_co_u32_e32 v68, vcc, s48, v66
	v_cvt_pk_bf16_f32 v70, v75, s0
	s_nop 0
	v_addc_co_u32_e32 v69, vcc, 0, v67, vcc
	global_store_short v[68:69], v70, off offset:512
	v_add_co_u32_e32 v68, vcc, 0x8000, v66
	v_cvt_pk_bf16_f32 v70, v76, s0
	s_nop 0
	v_addc_co_u32_e32 v69, vcc, 0, v67, vcc
	global_store_short v[68:69], v70, off offset:1024
	v_add_co_u32_e32 v68, vcc, s7, v66
	v_cvt_pk_bf16_f32 v70, v77, s0
	s_nop 0
	v_addc_co_u32_e32 v69, vcc, 0, v67, vcc
	global_store_short v[68:69], v70, off offset:1536
	v_lshl_add_u64 v[66:67], v[66:67], 0, s[52:53]
	v_cvt_pk_bf16_f32 v68, v78, s0
	global_store_short v[66:67], v68, off
	v_add_co_u32_e32 v68, vcc, 0x4000, v66
	v_cvt_pk_bf16_f32 v70, v79, s0
	s_nop 0
	v_addc_co_u32_e32 v69, vcc, 0, v67, vcc
	global_store_short v[68:69], v70, off offset:512
	v_add_co_u32_e32 v68, vcc, 0x8000, v66
	v_cvt_pk_bf16_f32 v70, v80, s0
	s_nop 0
	v_addc_co_u32_e32 v69, vcc, 0, v67, vcc
	global_store_short v[68:69], v70, off offset:1024
	v_add_co_u32_e32 v68, vcc, 0xc000, v66
	v_cvt_pk_bf16_f32 v70, v81, s0
	s_nop 0
	v_addc_co_u32_e32 v69, vcc, 0, v67, vcc
	v_lshl_add_u64 v[66:67], v[66:67], 0, s[52:53]
	global_store_short v[68:69], v70, off offset:1536

; #define STT(BASE, MUL) { bf16_t* q_ = (BASE) + (size_t)(4 * h) * TOK; _Pragma("unroll") for (int mi = 0; mi < 4; ++mi) _Pragma("unroll") for (int g = 0; g < 4; ++g) { \
;       _Pragma("unroll") for (int e = 0; e < 4; ++e) q_[(size_t)e * TOK] = f2bf(acc[mi][NI][4 * g + e] * (MUL)); q_ += (size_t)8 * TOK; asm volatile("" : "+v"(q_)); } }
; template <int NI> DI void inproj_epi_reg(const Params& p, int layer, int nt, int tok, int h, f32x16 (&acc)[4][2]) {
;     ...
;   } else if (nt < 20) {
;     bf16_t* VT = (bf16_t*)(p.ws + O_RVT) + (size_t)((nt - 16) * 128) * TOK + tok;
;     STT(VT, 1.f);
.LBB0_208:
	s_andn2_saveexec_b64 s[14:15], s[14:15]
	s_cbranch_execz .LBB0_210
	v_readlane_b32 s16, v253, 56
	v_readlane_b32 s17, v253, 57
	v_lshl_add_u32 v131, v237, 7, v232
	v_mov_b32_e32 v133, v181
	s_waitcnt vmcnt(0)
	v_mov_b64_e32 v[134:135], s[16:17]
	s_ashr_i32 s7, s6, 31
	v_mad_u64_u32 v[134:135], s[16:17], v131, s29, v[134:135]
	v_lshl_add_u64 v[136:137], v[132:133], 0, s[6:7]
	v_mul_u32_u24_e32 v131, 0x8400, v193
	v_lshl_add_u64 v[134:135], v[136:137], 1, v[134:135]
	v_lshlrev_b32_e32 v180, 1, v131
	v_lshl_add_u64 v[134:135], v[134:135], 0, v[180:181]
	v_cvt_pk_bf16_f32 v114, v114, s0
	global_store_short v[134:135], v114, off offset:512
	v_add_co_u32_e32 v114, vcc, s48, v134
	v_cvt_pk_bf16_f32 v131, v115, s0
	s_nop 0
	v_addc_co_u32_e32 v115, vcc, 0, v135, vcc
	s_mov_b32 s16, 0x8000
	global_store_short v[114:115], v131, off offset:1024
	v_add_co_u32_e32 v114, vcc, s16, v134
	v_cvt_pk_bf16_f32 v116, v116, s0
	s_nop 0
	v_addc_co_u32_e32 v115, vcc, 0, v135, vcc
	s_mov_b32 s7, 0xc000
	global_store_short v[114:115], v116, off offset:1536
	v_add_co_u32_e32 v114, vcc, s7, v134
	v_cvt_pk_bf16_f32 v116, v117, s0
	s_nop 0
	v_addc_co_u32_e32 v115, vcc, 0, v135, vcc
	s_mov_b64 s[18:19], 0x21200
	global_store_short v[114:115], v116, off offset:2048
	v_lshl_add_u64 v[114:115], v[134:135], 0, s[18:19]
	v_cvt_pk_bf16_f32 v116, v118, s0
	global_store_short v[114:115], v116, off
	v_add_co_u32_e32 v116, vcc, s48, v114
	v_cvt_pk_bf16_f32 v118, v119, s0
	s_nop 0
	v_addc_co_u32_e32 v117, vcc, 0, v115, vcc
	global_store_short v[116:117], v118, off offset:512
	v_add_co_u32_e32 v116, vcc, s16, v114
	v_cvt_pk_bf16_f32 v118, v120, s0
	s_nop 0
	v_addc_co_u32_e32 v117, vcc, 0, v115, vcc
	global_store_short v[116:117], v118, off offset:1024
	v_add_co_u32_e32 v116, vcc, s7, v114
	v_cvt_pk_bf16_f32 v118, v121, s0
	s_nop 0
	v_addc_co_u32_e32 v117, vcc, 0, v115, vcc
	s_mov_b64 s[18:19], 0x21000
	global_store_short v[116:117], v118, off offset:1536
	v_lshl_add_u64 v[114:115], v[114:115], 0, s[18:19]
	v_cvt_pk_bf16_f32 v116, v122, s0
	global_store_short v[114:115], v116, off
	v_add_co_u32_e32 v116, vcc, s48, v114
	v_cvt_pk_bf16_f32 v118, v123, s0
	s_nop 0
	v_addc_co_u32_e32 v117, vcc, 0, v115, vcc
	global_store_short v[116:117], v118, off offset:512
	v_add_co_u32_e32 v116, vcc, s16, v114
	v_cvt_pk_bf16_f32 v118, v124, s0
	s_nop 0
	v_addc_co_u32_e32 v117, vcc, 0, v115, vcc
	global_store_short v[116:117], v118, off offset:1024
	v_add_co_u32_e32 v116, vcc, s7, v114
	v_cvt_pk_bf16_f32 v118, v125, s0
	s_nop 0
	v_addc_co_u32_e32 v117, vcc, 0, v115, vcc
	global_store_short v[116:117], v118, off offset:1536
	v_lshl_add_u64 v[114:115], v[114:115], 0, s[18:19]
	v_cvt_pk_bf16_f32 v116, v126, s0
	global_store_short v[114:115], v116, off
	v_add_co_u32_e32 v116, vcc, s48, v114
	v_cvt_pk_bf16_f32 v118, v127, s0
	s_nop 0
	v_addc_co_u32_e32 v117, vcc, 0, v115, vcc
	global_store_short v[116:117], v118, off offset:512
	v_add_co_u32_e32 v116, vcc, s16, v114
	v_cvt_pk_bf16_f32 v118, v128, s0
	s_nop 0
	v_addc_co_u32_e32 v117, vcc, 0, v115, vcc
	global_store_short v[116:117], v118, off offset:1024
	v_add_co_u32_e32 v116, vcc, s7, v114
	v_cvt_pk_bf16_f32 v118, v129, s0
	s_nop 0
	v_addc_co_u32_e32 v117, vcc, 0, v115, vcc
	v_lshl_add_u64 v[114:115], v[114:115], 0, s[18:19]
	v_cvt_pk_bf16_f32 v98, v98, s0
	global_store_short v[116:117], v118, off offset:1536
	global_store_short v[114:115], v98, off
	v_add_co_u32_e32 v98, vcc, s48, v114
	v_cvt_pk_bf16_f32 v116, v99, s0
	s_nop 0
	v_addc_co_u32_e32 v99, vcc, 0, v115, vcc
	global_store_short v[98:99], v116, off offset:512
	v_add_co_u32_e32 v98, vcc, s16, v114
	v_cvt_pk_bf16_f32 v100, v100, s0
	s_nop 0
	v_addc_co_u32_e32 v99, vcc, 0, v115, vcc
	global_store_short v[98:99], v100, off offset:1024
	v_add_co_u32_e32 v98, vcc, s7, v114
	v_cvt_pk_bf16_f32 v100, v101, s0
	s_nop 0
	v_addc_co_u32_e32 v99, vcc, 0, v115, vcc
	global_store_short v[98:99], v100, off offset:1536
	v_lshl_add_u64 v[98:99], v[114:115], 0, s[18:19]
	v_cvt_pk_bf16_f32 v100, v102, s0
	global_store_short v[98:99], v100, off
	v_add_co_u32_e32 v100, vcc, s48, v98
	v_cvt_pk_bf16_f32 v102, v103, s0
	s_nop 0
	v_addc_co_u32_e32 v101, vcc, 0, v99, vcc
	global_store_short v[100:101], v102, off offset:512
	v_add_co_u32_e32 v100, vcc, s16, v98
	v_cvt_pk_bf16_f32 v102, v104, s0
	s_nop 0
	v_addc_co_u32_e32 v101, vcc, 0, v99, vcc
	global_store_short v[100:101], v102, off offset:1024
	v_add_co_u32_e32 v100, vcc, s7, v98
	v_cvt_pk_bf16_f32 v102, v105, s0
	s_nop 0
	v_addc_co_u32_e32 v101, vcc, 0, v99, vcc
	global_store_short v[100:101], v102, off offset:1536
	v_lshl_add_u64 v[98:99], v[98:99], 0, s[18:19]
	v_cvt_pk_bf16_f32 v100, v106, s0
	global_store_short v[98:99], v100, off
	v_add_co_u32_e32 v100, vcc, s48, v98
	v_cvt_pk_bf16_f32 v102, v107, s0
	s_nop 0
	v_addc_co_u32_e32 v101, vcc, 0, v99, vcc
	global_store_short v[100:101], v102, off offset:512
	v_add_co_u32_e32 v100, vcc, s16, v98
	v_cvt_pk_bf16_f32 v102, v108, s0
	s_nop 0
	v_addc_co_u32_e32 v101, vcc, 0, v99, vcc
	global_store_short v[100:101], v102, off offset:1024
	v_add_co_u32_e32 v100, vcc, s7, v98
	v_cvt_pk_bf16_f32 v102, v109, s0
	s_nop 0
	v_addc_co_u32_e32 v101, vcc, 0, v99, vcc
	global_store_short v[100:101], v102, off offset:1536
	v_lshl_add_u64 v[98:99], v[98:99], 0, s[18:19]
	v_cvt_pk_bf16_f32 v100, v110, s0
	global_store_short v[98:99], v100, off
	v_add_co_u32_e32 v100, vcc, s48, v98
	v_cvt_pk_bf16_f32 v102, v111, s0
	s_nop 0
	v_addc_co_u32_e32 v101, vcc, 0, v99, vcc
; #define STT(BASE, MUL) { bf16_t* q_ = (BASE) + (size_t)(4 * h) * TOK; _Pragma("unroll") for (int mi = 0; mi < 4; ++mi) _Pragma("unroll") for (int g = 0; g < 4; ++g) { \
;       _Pragma("unroll") for (int e = 0; e < 4; ++e) q_[(size_t)e * TOK] = f2bf(acc[mi][NI][4 * g + e] * (MUL)); q_ += (size_t)8 * TOK; asm volatile("" : "+v"(q_)); } }
; template <int NI> DI void inproj_epi_reg(const Params& p, int layer, int nt, int tok, int h, f32x16 (&acc)[4][2]) {
;     ...
;   } else if (nt < 20) {
;     bf16_t* VT = (bf16_t*)(p.ws + O_RVT) + (size_t)((nt - 16) * 128) * TOK + tok;
;     STT(VT, 1.f);
	global_store_short v[100:101], v102, off offset:512
	v_add_co_u32_e32 v100, vcc, s16, v98
	v_cvt_pk_bf16_f32 v102, v112, s0
	s_nop 0
	v_addc_co_u32_e32 v101, vcc, 0, v99, vcc
	global_store_short v[100:101], v102, off offset:1024
	v_add_co_u32_e32 v100, vcc, s7, v98
	v_cvt_pk_bf16_f32 v102, v113, s0
	s_nop 0
	v_addc_co_u32_e32 v101, vcc, 0, v99, vcc
	v_lshl_add_u64 v[98:99], v[98:99], 0, s[18:19]
	v_cvt_pk_bf16_f32 v82, v82, s0
	global_store_short v[100:101], v102, off offset:1536
	global_store_short v[98:99], v82, off
	v_add_co_u32_e32 v82, vcc, s48, v98
	v_cvt_pk_bf16_f32 v100, v83, s0
	s_nop 0
	v_addc_co_u32_e32 v83, vcc, 0, v99, vcc
	global_store_short v[82:83], v100, off offset:512
	v_add_co_u32_e32 v82, vcc, s16, v98
	v_cvt_pk_bf16_f32 v84, v84, s0
	s_nop 0
	v_addc_co_u32_e32 v83, vcc, 0, v99, vcc
	global_store_short v[82:83], v84, off offset:1024
	v_add_co_u32_e32 v82, vcc, s7, v98
	v_cvt_pk_bf16_f32 v84, v85, s0
	s_nop 0
	v_addc_co_u32_e32 v83, vcc, 0, v99, vcc
	global_store_short v[82:83], v84, off offset:1536
	v_lshl_add_u64 v[82:83], v[98:99], 0, s[18:19]
	v_cvt_pk_bf16_f32 v84, v86, s0
	global_store_short v[82:83], v84, off
	v_add_co_u32_e32 v84, vcc, s48, v82
	v_cvt_pk_bf16_f32 v86, v87, s0
	s_nop 0
	v_addc_co_u32_e32 v85, vcc, 0, v83, vcc
	global_store_short v[84:85], v86, off offset:512
	v_add_co_u32_e32 v84, vcc, s16, v82
	v_cvt_pk_bf16_f32 v86, v88, s0
	s_nop 0
	v_addc_co_u32_e32 v85, vcc, 0, v83, vcc
	global_store_short v[84:85], v86, off offset:1024
	v_add_co_u32_e32 v84, vcc, s7, v82
	v_cvt_pk_bf16_f32 v86, v89, s0
	s_nop 0
	v_addc_co_u32_e32 v85, vcc, 0, v83, vcc
	global_store_short v[84:85], v86, off offset:1536
	v_lshl_add_u64 v[82:83], v[82:83], 0, s[18:19]
	v_cvt_pk_bf16_f32 v84, v90, s0
	global_store_short v[82:83], v84, off
	v_add_co_u32_e32 v84, vcc, s48, v82
	v_cvt_pk_bf16_f32 v86, v91, s0
	s_nop 0
	v_addc_co_u32_e32 v85, vcc, 0, v83, vcc
	global_store_short v[84:85], v86, off offset:512
	v_add_co_u32_e32 v84, vcc, s16, v82
	v_cvt_pk_bf16_f32 v86, v92, s0
	s_nop 0
	v_addc_co_u32_e32 v85, vcc, 0, v83, vcc
	global_store_short v[84:85], v86, off offset:1024
	v_add_co_u32_e32 v84, vcc, s7, v82
	v_cvt_pk_bf16_f32 v86, v93, s0
	s_nop 0
	v_addc_co_u32_e32 v85, vcc, 0, v83, vcc
	global_store_short v[84:85], v86, off offset:1536
	v_lshl_add_u64 v[82:83], v[82:83], 0, s[18:19]
	v_cvt_pk_bf16_f32 v84, v94, s0
	global_store_short v[82:83], v84, off
	v_add_co_u32_e32 v84, vcc, s48, v82
	v_cvt_pk_bf16_f32 v86, v95, s0
	s_nop 0
	v_addc_co_u32_e32 v85, vcc, 0, v83, vcc
	global_store_short v[84:85], v86, off offset:512
	v_add_co_u32_e32 v84, vcc, s16, v82
	v_cvt_pk_bf16_f32 v86, v96, s0
	s_nop 0
	v_addc_co_u32_e32 v85, vcc, 0, v83, vcc
	global_store_short v[84:85], v86, off offset:1024
	v_add_co_u32_e32 v84, vcc, s7, v82
	v_cvt_pk_bf16_f32 v86, v97, s0
	s_nop 0
	v_addc_co_u32_e32 v85, vcc, 0, v83, vcc
	v_lshl_add_u64 v[82:83], v[82:83], 0, s[18:19]
	v_cvt_pk_bf16_f32 v66, v66, s0
	global_store_short v[84:85], v86, off offset:1536
	global_store_short v[82:83], v66, off
	v_add_co_u32_e32 v66, vcc, s48, v82
	v_cvt_pk_bf16_f32 v84, v67, s0
	s_nop 0
	v_addc_co_u32_e32 v67, vcc, 0, v83, vcc
	global_store_short v[66:67], v84, off offset:512
	v_add_co_u32_e32 v66, vcc, s16, v82
	v_cvt_pk_bf16_f32 v68, v68, s0
	s_nop 0
	v_addc_co_u32_e32 v67, vcc, 0, v83, vcc
	global_store_short v[66:67], v68, off offset:1024
	v_add_co_u32_e32 v66, vcc, s7, v82
	v_cvt_pk_bf16_f32 v68, v69, s0
	s_nop 0
	v_addc_co_u32_e32 v67, vcc, 0, v83, vcc
	global_store_short v[66:67], v68, off offset:1536
	v_lshl_add_u64 v[66:67], v[82:83], 0, s[18:19]
	v_cvt_pk_bf16_f32 v68, v70, s0
	global_store_short v[66:67], v68, off
	v_add_co_u32_e32 v68, vcc, s48, v66
	v_cvt_pk_bf16_f32 v70, v71, s0
	s_nop 0
	v_addc_co_u32_e32 v69, vcc, 0, v67, vcc
	global_store_short v[68:69], v70, off offset:512
	v_add_co_u32_e32 v68, vcc, s16, v66
	v_cvt_pk_bf16_f32 v70, v72, s0
	s_nop 0
	v_addc_co_u32_e32 v69, vcc, 0, v67, vcc
	global_store_short v[68:69], v70, off offset:1024
	v_add_co_u32_e32 v68, vcc, s7, v66
	v_cvt_pk_bf16_f32 v70, v73, s0
	s_nop 0
	v_addc_co_u32_e32 v69, vcc, 0, v67, vcc
	global_store_short v[68:69], v70, off offset:1536
	v_lshl_add_u64 v[66:67], v[66:67], 0, s[18:19]
	v_cvt_pk_bf16_f32 v68, v74, s0
	global_store_short v[66:67], v68, off
	v_add_co_u32_e32 v68, vcc, s48, v66
	v_cvt_pk_bf16_f32 v70, v75, s0
	s_nop 0
	v_addc_co_u32_e32 v69, vcc, 0, v67, vcc
	global_store_short v[68:69], v70, off offset:512
	v_add_co_u32_e32 v68, vcc, 0x8000, v66
	v_cvt_pk_bf16_f32 v70, v76, s0
	s_nop 0
	v_addc_co_u32_e32 v69, vcc, 0, v67, vcc
	global_store_short v[68:69], v70, off offset:1024
	v_add_co_u32_e32 v68, vcc, s7, v66
	v_cvt_pk_bf16_f32 v70, v77, s0
	s_nop 0
	v_addc_co_u32_e32 v69, vcc, 0, v67, vcc
	global_store_short v[68:69], v70, off offset:1536
	v_lshl_add_u64 v[66:67], v[66:67], 0, s[18:19]
	v_cvt_pk_bf16_f32 v68, v78, s0
	global_store_short v[66:67], v68, off
	v_add_co_u32_e32 v68, vcc, 0x4000, v66
	v_cvt_pk_bf16_f32 v70, v79, s0
	s_nop 0
	v_addc_co_u32_e32 v69, vcc, 0, v67, vcc
	global_store_short v[68:69], v70, off offset:512
	v_add_co_u32_e32 v68, vcc, 0x8000, v66
	v_cvt_pk_bf16_f32 v70, v80, s0
	s_nop 0
	v_addc_co_u32_e32 v69, vcc, 0, v67, vcc
	global_store_short v[68:69], v70, off offset:1024
	v_add_co_u32_e32 v68, vcc, 0xc000, v66
	v_cvt_pk_bf16_f32 v70, v81, s0
	s_nop 0
	v_addc_co_u32_e32 v69, vcc, 0, v67, vcc
	v_lshl_add_u64 v[66:67], v[66:67], 0, s[18:19]
	global_store_short v[68:69], v70, off offset:1536

; DI float ex2(float x) { return __builtin_amdgcn_exp2f(x); }
; #define ST4(BASE) { _Pragma("unroll") for (int mi = 0; mi < 4; ++mi) _Pragma("unroll") for (int g = 0; g < 4; ++g) { \
;       u32x2 o_; o_.x = pack2(acc[mi][NI][4 * g], acc[mi][NI][4 * g + 1]); o_.y = pack2(acc[mi][NI][4 * g + 2], acc[mi][NI][4 * g + 3]); *(u32x2*)((BASE) + 32 * mi + 8 * g + 4 * h) = o_; } }
; template <int NI> DI void inproj_epi_reg(const Params& p, int layer, int nt, int tok, int h, f32x16 (&acc)[4][2]) {
;     ...
;     } else {
;       const float scale = 0.08838834764831845f;
;       const float lgf = scal[layer * 8 + hd], lgb = scal[layer * 8 + 4 + hd];
;       const int j = tok & 127;
;       const float df = ex2((float)(127 - j) * lgf * LOG2E), db = ex2((float)j * lgb * LOG2E);
; #pragma unroll
;       for (int mi = 0; mi < 4; ++mi)
; #pragma unroll
;         for (int reg = 0; reg < 16; ++reg) acc[mi][NI][reg] *= scale;
;       bf16_t* RK = (bf16_t*)(p.ws + O_RK) + (size_t)tok * 512 + hd * 128;
;       ST4(RK);
;       bf16_t* KF = (bf16_t*)(p.ws + O_RKTF) + (size_t)(hd * 128) * TOK + tok;
;       bf16_t* KB = (bf16_t*)(p.ws + O_RKTB) + (size_t)(hd * 128) * TOK + tok;
.LBB0_214:
	s_andn2_saveexec_b64 s[14:15], s[14:15]
	s_cbranch_execz .LBB0_216
	v_readlane_b32 s7, v255, 0
	v_readlane_b32 s16, v252, 36
	v_mov_b32_e32 v81, v181
	v_or_b32_e32 v80, s7, v133
	v_readlane_b32 s17, v252, 37
	s_movk_i32 s7, 0x7f
	v_bitop3_b32 v91, v131, s7, v233 bitop3:0x6c
	v_lshl_add_u64 v[80:81], v[80:81], 2, s[16:17]
	global_load_dword v90, v[80:81], off
	s_nop 0
	global_load_dword v80, v[80:81], off offset:16
	v_and_b32_e32 v81, 0x5f, v131
	v_cvt_f32_ubyte0_e32 v91, v91
	v_cvt_f32_ubyte0_e32 v81, v81
	s_mov_b32 s16, 0x3db504f3
	v_pk_mul_f32 v[146:147], v[134:135], s[16:17] op_sel_hi:[1,0]
	v_pk_mul_f32 v[142:143], v[114:115], s[16:17] op_sel_hi:[1,0]
	v_pk_mul_f32 v[140:141], v[116:117], s[16:17] op_sel_hi:[1,0]
	v_pk_mul_f32 v[138:139], v[118:119], s[16:17] op_sel_hi:[1,0]
	v_pk_mul_f32 v[136:137], v[120:121], s[16:17] op_sel_hi:[1,0]
	v_pk_mul_f32 v[134:135], v[122:123], s[16:17] op_sel_hi:[1,0]
	v_pk_mul_f32 v[124:125], v[124:125], s[16:17] op_sel_hi:[1,0]
	v_pk_mul_f32 v[122:123], v[126:127], s[16:17] op_sel_hi:[1,0]
	v_pk_mul_f32 v[120:121], v[98:99], s[16:17] op_sel_hi:[1,0]
	v_pk_mul_f32 v[118:119], v[100:101], s[16:17] op_sel_hi:[1,0]
	v_pk_mul_f32 v[116:117], v[102:103], s[16:17] op_sel_hi:[1,0]
	v_pk_mul_f32 v[114:115], v[104:105], s[16:17] op_sel_hi:[1,0]
	v_pk_mul_f32 v[104:105], v[106:107], s[16:17] op_sel_hi:[1,0]
	v_pk_mul_f32 v[102:103], v[108:109], s[16:17] op_sel_hi:[1,0]
	v_pk_mul_f32 v[100:101], v[110:111], s[16:17] op_sel_hi:[1,0]
	v_pk_mul_f32 v[98:99], v[112:113], s[16:17] op_sel_hi:[1,0]
	v_pk_mul_f32 v[96:97], v[128:129], s[16:17] op_sel_hi:[1,0]
	v_pk_mul_f32 v[94:95], v[82:83], s[16:17] op_sel_hi:[1,0]
	v_pk_mul_f32 v[92:93], v[84:85], s[16:17] op_sel_hi:[1,0]
	v_pk_mul_f32 v[88:89], v[88:89], s[16:17] op_sel_hi:[1,0]
	v_pk_mul_f32 v[84:85], v[76:77], s[16:17] op_sel_hi:[1,0]
	v_pk_mul_f32 v[82:83], v[78:79], s[16:17] op_sel_hi:[1,0]
	v_pk_mul_f32 v[78:79], v[68:69], s[16:17] op_sel_hi:[1,0]
	v_pk_mul_f32 v[76:77], v[70:71], s[16:17] op_sel_hi:[1,0]
	v_pk_mul_f32 v[70:71], v[148:149], s[16:17] op_sel_hi:[1,0]
	v_pk_mul_f32 v[68:69], v[150:151], s[16:17] op_sel_hi:[1,0]
	v_mov_b32_e32 v155, v181
	v_cvt_pk_bf16_f32 v108, v146, v147
	v_cvt_pk_bf16_f32 v109, v142, v143
	v_lshlrev_b32_e32 v111, 7, v133
	v_mov_b32_e32 v133, v181
	s_ashr_i32 s7, s6, 31
	s_mov_b64 s[18:19], 0x21200
	s_mov_b64 s[44:45], 0x21000
	s_waitcnt vmcnt(0)
	v_mul_f32_e32 v90, v90, v91
	v_mul_f32_e32 v131, 0x3fb8aa3b, v90
	v_mul_f32_e32 v80, v80, v81
	v_mul_f32_e32 v156, 0x3fb8aa3b, v80
	v_pk_mul_f32 v[90:91], v[86:87], s[16:17] op_sel_hi:[1,0]
	v_pk_mul_f32 v[86:87], v[74:75], s[16:17] op_sel_hi:[1,0]
	v_pk_mul_f32 v[80:81], v[66:67], s[16:17] op_sel_hi:[1,0]
	v_pk_mul_f32 v[74:75], v[72:73], s[16:17] op_sel_hi:[1,0]
	v_pk_mul_f32 v[72:73], v[144:145], s[16:17] op_sel_hi:[1,0]
	v_pk_mul_f32 v[66:67], v[152:153], s[16:17] op_sel_hi:[1,0]
	v_exp_f32_e32 v110, v131
	v_ashrrev_i32_e32 v131, 31, v130
	v_readlane_b32 s16, v253, 60
	v_lshlrev_b64 v[106:107], 10, v[130:131]
	v_readlane_b32 s17, v253, 61
	s_nop 1
	v_lshl_add_u64 v[106:107], s[16:17], 0, v[106:107]
	v_lshl_add_u64 v[106:107], v[106:107], 0, v[180:181]
	v_lshl_add_u64 v[106:107], v[106:107], 0, v[154:155]
	global_store_dwordx2 v[106:107], v[108:109], off
	v_cvt_pk_bf16_f32 v108, v140, v141
	v_cvt_pk_bf16_f32 v109, v138, v139
	global_store_dwordx2 v[106:107], v[108:109], off offset:16
	v_cvt_pk_bf16_f32 v108, v136, v137
	v_cvt_pk_bf16_f32 v109, v134, v135
	global_store_dwordx2 v[106:107], v[108:109], off offset:32
	v_cvt_pk_bf16_f32 v108, v124, v125
	v_cvt_pk_bf16_f32 v109, v122, v123
	global_store_dwordx2 v[106:107], v[108:109], off offset:48
	v_cvt_pk_bf16_f32 v108, v120, v121
	v_cvt_pk_bf16_f32 v109, v118, v119
	global_store_dwordx2 v[106:107], v[108:109], off offset:64
	v_cvt_pk_bf16_f32 v108, v116, v117
	v_cvt_pk_bf16_f32 v109, v114, v115
	global_store_dwordx2 v[106:107], v[108:109], off offset:80
	v_cvt_pk_bf16_f32 v108, v104, v105
	v_cvt_pk_bf16_f32 v109, v102, v103
	global_store_dwordx2 v[106:107], v[108:109], off offset:96
	v_cvt_pk_bf16_f32 v108, v100, v101
	v_cvt_pk_bf16_f32 v109, v98, v99
	global_store_dwordx2 v[106:107], v[108:109], off offset:112
	v_cvt_pk_bf16_f32 v108, v96, v97
	v_cvt_pk_bf16_f32 v109, v94, v95
	global_store_dwordx2 v[106:107], v[108:109], off offset:128
	v_cvt_pk_bf16_f32 v108, v92, v93
	v_cvt_pk_bf16_f32 v109, v90, v91
	global_store_dwordx2 v[106:107], v[108:109], off offset:144
	v_cvt_pk_bf16_f32 v108, v88, v89
	v_cvt_pk_bf16_f32 v109, v86, v87
	global_store_dwordx2 v[106:107], v[108:109], off offset:160
	v_cvt_pk_bf16_f32 v108, v84, v85
	v_cvt_pk_bf16_f32 v109, v82, v83
	global_store_dwordx2 v[106:107], v[108:109], off offset:176
	v_cvt_pk_bf16_f32 v108, v80, v81
	v_cvt_pk_bf16_f32 v109, v78, v79
	global_store_dwordx2 v[106:107], v[108:109], off offset:192
	v_cvt_pk_bf16_f32 v108, v76, v77
	v_cvt_pk_bf16_f32 v109, v74, v75
	global_store_dwordx2 v[106:107], v[108:109], off offset:208
	v_cvt_pk_bf16_f32 v108, v72, v73
	v_cvt_pk_bf16_f32 v109, v70, v71
	global_store_dwordx2 v[106:107], v[108:109], off offset:224
	v_cvt_pk_bf16_f32 v108, v68, v69
	v_cvt_pk_bf16_f32 v109, v66, v67
	global_store_dwordx2 v[106:107], v[108:109], off offset:240
	v_mul_u32_u24_e32 v106, 0x2100, v111
	v_readlane_b32 s16, v253, 62
	v_lshlrev_b32_e32 v180, 1, v106
	v_readlane_b32 s17, v253, 63
	v_lshl_add_u64 v[106:107], v[132:133], 0, s[6:7]
	v_lshlrev_b64 v[106:107], 1, v[106:107]
	v_lshl_add_u64 v[108:109], s[16:17], 0, v[180:181]
	v_readlane_b32 s16, v254, 0
	v_readlane_b32 s17, v254, 1
	v_mul_u32_u24_e32 v111, 0x8400, v193
	v_lshl_add_u64 v[112:113], v[108:109], 0, v[106:107]
; #define STT(BASE, MUL) { bf16_t* q_ = (BASE) + (size_t)(4 * h) * TOK; _Pragma("unroll") for (int mi = 0; mi < 4; ++mi) _Pragma("unroll") for (int g = 0; g < 4; ++g) { \
;       _Pragma("unroll") for (int e = 0; e < 4; ++e) q_[(size_t)e * TOK] = f2bf(acc[mi][NI][4 * g + e] * (MUL)); q_ += (size_t)8 * TOK; asm volatile("" : "+v"(q_)); } }
; template <int NI> DI void inproj_epi_reg(const Params& p, int layer, int nt, int tok, int h, f32x16 (&acc)[4][2]) {
;     ...
;       bf16_t* KF = (bf16_t*)(p.ws + O_RKTF) + (size_t)(hd * 128) * TOK + tok;
;       bf16_t* KB = (bf16_t*)(p.ws + O_RKTB) + (size_t)(hd * 128) * TOK + tok;
;       STT(KF, df);
;       STT(KB, db);
	v_lshl_add_u64 v[108:109], s[16:17], 0, v[180:181]
	v_lshlrev_b32_e32 v180, 1, v111
	v_mul_f32_e32 v111, v146, v110
	v_lshl_add_u64 v[112:113], v[112:113], 0, v[180:181]
	v_cvt_pk_bf16_f32 v111, v111, s0
	global_store_short v[112:113], v111, off offset:512
	v_mul_f32_e32 v111, v147, v110
	v_add_co_u32_e32 v126, vcc, s48, v112
	v_cvt_pk_bf16_f32 v111, v111, s0
	s_nop 0
	v_addc_co_u32_e32 v127, vcc, 0, v113, vcc
	s_mov_b32 s16, 0x8000
	global_store_short v[126:127], v111, off offset:1024
	v_mul_f32_e32 v111, v142, v110
	v_add_co_u32_e32 v126, vcc, s16, v112
	v_cvt_pk_bf16_f32 v111, v111, s0
	s_nop 0
	v_addc_co_u32_e32 v127, vcc, 0, v113, vcc
	s_mov_b32 s7, 0xc000
	global_store_short v[126:127], v111, off offset:1536
	v_mul_f32_e32 v111, v143, v110
	v_add_co_u32_e32 v126, vcc, s7, v112
	v_cvt_pk_bf16_f32 v111, v111, s0
	s_nop 0
	v_addc_co_u32_e32 v127, vcc, 0, v113, vcc
	global_store_short v[126:127], v111, off offset:2048
	v_mul_f32_e32 v111, v140, v110
	v_lshl_add_u64 v[112:113], v[112:113], 0, s[18:19]
	v_cvt_pk_bf16_f32 v111, v111, s0
	global_store_short v[112:113], v111, off
	v_mul_f32_e32 v111, v141, v110
	v_add_co_u32_e32 v126, vcc, s48, v112
	v_cvt_pk_bf16_f32 v111, v111, s0
	s_nop 0
	v_addc_co_u32_e32 v127, vcc, 0, v113, vcc
	global_store_short v[126:127], v111, off offset:512
	v_mul_f32_e32 v111, v138, v110
	v_add_co_u32_e32 v126, vcc, s16, v112
	v_cvt_pk_bf16_f32 v111, v111, s0
	s_nop 0
	v_addc_co_u32_e32 v127, vcc, 0, v113, vcc
	global_store_short v[126:127], v111, off offset:1024
	v_mul_f32_e32 v111, v139, v110
	v_add_co_u32_e32 v126, vcc, s7, v112
	v_cvt_pk_bf16_f32 v111, v111, s0
	s_nop 0
	v_addc_co_u32_e32 v127, vcc, 0, v113, vcc
	global_store_short v[126:127], v111, off offset:1536
	v_mul_f32_e32 v111, v136, v110
	v_lshl_add_u64 v[112:113], v[112:113], 0, s[44:45]
	v_cvt_pk_bf16_f32 v111, v111, s0
	global_store_short v[112:113], v111, off
	v_mul_f32_e32 v111, v137, v110
	v_add_co_u32_e32 v126, vcc, s48, v112
	v_cvt_pk_bf16_f32 v111, v111, s0
	s_nop 0
	v_addc_co_u32_e32 v127, vcc, 0, v113, vcc
	global_store_short v[126:127], v111, off offset:512
	v_mul_f32_e32 v111, v134, v110
	v_add_co_u32_e32 v126, vcc, s16, v112
	v_cvt_pk_bf16_f32 v111, v111, s0
	s_nop 0
	v_addc_co_u32_e32 v127, vcc, 0, v113, vcc
	global_store_short v[126:127], v111, off offset:1024
	v_mul_f32_e32 v111, v135, v110
	v_add_co_u32_e32 v126, vcc, s7, v112
	v_cvt_pk_bf16_f32 v111, v111, s0
	s_nop 0
	v_addc_co_u32_e32 v127, vcc, 0, v113, vcc
	global_store_short v[126:127], v111, off offset:1536
	v_mul_f32_e32 v111, v124, v110
	v_lshl_add_u64 v[112:113], v[112:113], 0, s[44:45]
	v_cvt_pk_bf16_f32 v111, v111, s0
	global_store_short v[112:113], v111, off
	v_mul_f32_e32 v111, v125, v110
	v_add_co_u32_e32 v126, vcc, s48, v112
	v_cvt_pk_bf16_f32 v111, v111, s0
	s_nop 0
	v_addc_co_u32_e32 v127, vcc, 0, v113, vcc
	global_store_short v[126:127], v111, off offset:512
	v_mul_f32_e32 v111, v122, v110
	v_add_co_u32_e32 v126, vcc, s16, v112
	v_cvt_pk_bf16_f32 v111, v111, s0
	s_nop 0
	v_addc_co_u32_e32 v127, vcc, 0, v113, vcc
	global_store_short v[126:127], v111, off offset:1024
	v_mul_f32_e32 v111, v123, v110
	v_add_co_u32_e32 v126, vcc, s7, v112
	v_cvt_pk_bf16_f32 v111, v111, s0
	s_nop 0
	v_addc_co_u32_e32 v127, vcc, 0, v113, vcc
	global_store_short v[126:127], v111, off offset:1536
	v_mul_f32_e32 v111, v120, v110
	v_lshl_add_u64 v[112:113], v[112:113], 0, s[44:45]
	v_cvt_pk_bf16_f32 v111, v111, s0
	global_store_short v[112:113], v111, off
	v_mul_f32_e32 v111, v121, v110
	v_add_co_u32_e32 v126, vcc, s48, v112
	v_cvt_pk_bf16_f32 v111, v111, s0
	s_nop 0
	v_addc_co_u32_e32 v127, vcc, 0, v113, vcc
	global_store_short v[126:127], v111, off offset:512
	v_mul_f32_e32 v111, v118, v110
	v_add_co_u32_e32 v126, vcc, s16, v112
	v_cvt_pk_bf16_f32 v111, v111, s0
	s_nop 0
	v_addc_co_u32_e32 v127, vcc, 0, v113, vcc
	global_store_short v[126:127], v111, off offset:1024
	v_mul_f32_e32 v111, v119, v110
	v_add_co_u32_e32 v126, vcc, s7, v112
	v_cvt_pk_bf16_f32 v111, v111, s0
	s_nop 0
	v_addc_co_u32_e32 v127, vcc, 0, v113, vcc
	global_store_short v[126:127], v111, off offset:1536
	v_mul_f32_e32 v111, v116, v110
	v_lshl_add_u64 v[112:113], v[112:113], 0, s[44:45]
	v_cvt_pk_bf16_f32 v111, v111, s0
	global_store_short v[112:113], v111, off
	v_mul_f32_e32 v111, v117, v110
	v_add_co_u32_e32 v126, vcc, s48, v112
	v_cvt_pk_bf16_f32 v111, v111, s0
	s_nop 0
	v_addc_co_u32_e32 v127, vcc, 0, v113, vcc
	global_store_short v[126:127], v111, off offset:512
	v_mul_f32_e32 v111, v114, v110
	v_add_co_u32_e32 v126, vcc, s16, v112
	v_cvt_pk_bf16_f32 v111, v111, s0
	s_nop 0
	v_addc_co_u32_e32 v127, vcc, 0, v113, vcc
	global_store_short v[126:127], v111, off offset:1024
	v_mul_f32_e32 v111, v115, v110
	v_add_co_u32_e32 v126, vcc, s7, v112
	v_cvt_pk_bf16_f32 v111, v111, s0
	s_nop 0
	v_addc_co_u32_e32 v127, vcc, 0, v113, vcc
	global_store_short v[126:127], v111, off offset:1536
	v_mul_f32_e32 v111, v104, v110
	v_lshl_add_u64 v[112:113], v[112:113], 0, s[44:45]
	v_cvt_pk_bf16_f32 v111, v111, s0
	global_store_short v[112:113], v111, off
	v_mul_f32_e32 v111, v105, v110
	v_add_co_u32_e32 v126, vcc, s48, v112
	v_cvt_pk_bf16_f32 v111, v111, s0
	s_nop 0
	v_addc_co_u32_e32 v127, vcc, 0, v113, vcc
	global_store_short v[126:127], v111, off offset:512
	v_mul_f32_e32 v111, v102, v110
	v_add_co_u32_e32 v126, vcc, s16, v112
	v_cvt_pk_bf16_f32 v111, v111, s0
	s_nop 0
	v_addc_co_u32_e32 v127, vcc, 0, v113, vcc
	global_store_short v[126:127], v111, off offset:1024
	v_mul_f32_e32 v111, v103, v110
	v_add_co_u32_e32 v126, vcc, s7, v112
	v_cvt_pk_bf16_f32 v111, v111, s0
	s_nop 0
	v_addc_co_u32_e32 v127, vcc, 0, v113, vcc
; #define STT(BASE, MUL) { bf16_t* q_ = (BASE) + (size_t)(4 * h) * TOK; _Pragma("unroll") for (int mi = 0; mi < 4; ++mi) _Pragma("unroll") for (int g = 0; g < 4; ++g) { \
;       _Pragma("unroll") for (int e = 0; e < 4; ++e) q_[(size_t)e * TOK] = f2bf(acc[mi][NI][4 * g + e] * (MUL)); q_ += (size_t)8 * TOK; asm volatile("" : "+v"(q_)); } }
; template <int NI> DI void inproj_epi_reg(const Params& p, int layer, int nt, int tok, int h, f32x16 (&acc)[4][2]) {
;     ...
;       STT(KF, df);
;       STT(KB, db);
	global_store_short v[126:127], v111, off offset:1536
	v_mul_f32_e32 v111, v100, v110
	v_lshl_add_u64 v[112:113], v[112:113], 0, s[44:45]
	v_cvt_pk_bf16_f32 v111, v111, s0
	global_store_short v[112:113], v111, off
	v_mul_f32_e32 v111, v101, v110
	v_add_co_u32_e32 v126, vcc, s48, v112
	v_cvt_pk_bf16_f32 v111, v111, s0
	s_nop 0
	v_addc_co_u32_e32 v127, vcc, 0, v113, vcc
	global_store_short v[126:127], v111, off offset:512
	v_mul_f32_e32 v111, v98, v110
	v_add_co_u32_e32 v126, vcc, s16, v112
	v_cvt_pk_bf16_f32 v111, v111, s0
	s_nop 0
	v_addc_co_u32_e32 v127, vcc, 0, v113, vcc
	global_store_short v[126:127], v111, off offset:1024
	v_mul_f32_e32 v111, v99, v110
	v_add_co_u32_e32 v126, vcc, s7, v112
	v_cvt_pk_bf16_f32 v111, v111, s0
	s_nop 0
	v_addc_co_u32_e32 v127, vcc, 0, v113, vcc
	global_store_short v[126:127], v111, off offset:1536
	v_mul_f32_e32 v111, v96, v110
	v_lshl_add_u64 v[112:113], v[112:113], 0, s[44:45]
	v_cvt_pk_bf16_f32 v111, v111, s0
	global_store_short v[112:113], v111, off
	v_mul_f32_e32 v111, v97, v110
	v_add_co_u32_e32 v126, vcc, s48, v112
	v_cvt_pk_bf16_f32 v111, v111, s0
	s_nop 0
	v_addc_co_u32_e32 v127, vcc, 0, v113, vcc
	global_store_short v[126:127], v111, off offset:512
	v_mul_f32_e32 v111, v94, v110
	v_add_co_u32_e32 v126, vcc, s16, v112
	v_cvt_pk_bf16_f32 v111, v111, s0
	s_nop 0
	v_addc_co_u32_e32 v127, vcc, 0, v113, vcc
	global_store_short v[126:127], v111, off offset:1024
	v_mul_f32_e32 v111, v95, v110
	v_add_co_u32_e32 v126, vcc, s7, v112
	v_cvt_pk_bf16_f32 v111, v111, s0
	s_nop 0
	v_addc_co_u32_e32 v127, vcc, 0, v113, vcc
	global_store_short v[126:127], v111, off offset:1536
	v_mul_f32_e32 v111, v92, v110
	v_lshl_add_u64 v[112:113], v[112:113], 0, s[44:45]
	v_cvt_pk_bf16_f32 v111, v111, s0
	global_store_short v[112:113], v111, off
	v_mul_f32_e32 v111, v93, v110
	v_add_co_u32_e32 v126, vcc, s48, v112
	v_cvt_pk_bf16_f32 v111, v111, s0
	s_nop 0
	v_addc_co_u32_e32 v127, vcc, 0, v113, vcc
	global_store_short v[126:127], v111, off offset:512
	v_mul_f32_e32 v111, v90, v110
	v_add_co_u32_e32 v126, vcc, s16, v112
	v_cvt_pk_bf16_f32 v111, v111, s0
	s_nop 0
	v_addc_co_u32_e32 v127, vcc, 0, v113, vcc
	global_store_short v[126:127], v111, off offset:1024
	v_mul_f32_e32 v111, v91, v110
	v_add_co_u32_e32 v126, vcc, s7, v112
	v_cvt_pk_bf16_f32 v111, v111, s0
	s_nop 0
	v_addc_co_u32_e32 v127, vcc, 0, v113, vcc
	global_store_short v[126:127], v111, off offset:1536
	v_mul_f32_e32 v111, v88, v110
	v_lshl_add_u64 v[112:113], v[112:113], 0, s[44:45]
	v_cvt_pk_bf16_f32 v111, v111, s0
	global_store_short v[112:113], v111, off
	v_mul_f32_e32 v111, v89, v110
	v_add_co_u32_e32 v126, vcc, s48, v112
	v_cvt_pk_bf16_f32 v111, v111, s0
	s_nop 0
	v_addc_co_u32_e32 v127, vcc, 0, v113, vcc
	global_store_short v[126:127], v111, off offset:512
	v_mul_f32_e32 v111, v86, v110
	v_add_co_u32_e32 v126, vcc, s16, v112
	v_cvt_pk_bf16_f32 v111, v111, s0
	s_nop 0
	v_addc_co_u32_e32 v127, vcc, 0, v113, vcc
	global_store_short v[126:127], v111, off offset:1024
	v_mul_f32_e32 v111, v87, v110
	v_add_co_u32_e32 v126, vcc, s7, v112
	v_cvt_pk_bf16_f32 v111, v111, s0
	s_nop 0
	v_addc_co_u32_e32 v127, vcc, 0, v113, vcc
	global_store_short v[126:127], v111, off offset:1536
	v_mul_f32_e32 v111, v84, v110
	v_lshl_add_u64 v[112:113], v[112:113], 0, s[44:45]
	v_cvt_pk_bf16_f32 v111, v111, s0
	global_store_short v[112:113], v111, off
	v_mul_f32_e32 v111, v85, v110
	v_add_co_u32_e32 v126, vcc, s48, v112
	v_cvt_pk_bf16_f32 v111, v111, s0
	s_nop 0
	v_addc_co_u32_e32 v127, vcc, 0, v113, vcc
	global_store_short v[126:127], v111, off offset:512
	v_mul_f32_e32 v111, v82, v110
	v_add_co_u32_e32 v126, vcc, s16, v112
	v_cvt_pk_bf16_f32 v111, v111, s0
	s_nop 0
	v_addc_co_u32_e32 v127, vcc, 0, v113, vcc
	global_store_short v[126:127], v111, off offset:1024
	v_mul_f32_e32 v111, v83, v110
	v_add_co_u32_e32 v126, vcc, s7, v112
	v_cvt_pk_bf16_f32 v111, v111, s0
	s_nop 0
	v_addc_co_u32_e32 v127, vcc, 0, v113, vcc
	global_store_short v[126:127], v111, off offset:1536
	v_mul_f32_e32 v111, v80, v110
	v_lshl_add_u64 v[112:113], v[112:113], 0, s[44:45]
	v_cvt_pk_bf16_f32 v111, v111, s0
	global_store_short v[112:113], v111, off
	v_mul_f32_e32 v111, v81, v110
	v_add_co_u32_e32 v126, vcc, s48, v112
	v_cvt_pk_bf16_f32 v111, v111, s0
	s_nop 0
	v_addc_co_u32_e32 v127, vcc, 0, v113, vcc
	global_store_short v[126:127], v111, off offset:512
	v_mul_f32_e32 v111, v78, v110
	v_add_co_u32_e32 v126, vcc, s16, v112
	v_cvt_pk_bf16_f32 v111, v111, s0
	s_nop 0
	v_addc_co_u32_e32 v127, vcc, 0, v113, vcc
	global_store_short v[126:127], v111, off offset:1024
	v_mul_f32_e32 v111, v79, v110
	v_add_co_u32_e32 v126, vcc, s7, v112
	v_cvt_pk_bf16_f32 v111, v111, s0
	s_nop 0
	v_addc_co_u32_e32 v127, vcc, 0, v113, vcc
	global_store_short v[126:127], v111, off offset:1536
	v_mul_f32_e32 v111, v76, v110
	v_lshl_add_u64 v[112:113], v[112:113], 0, s[44:45]
	v_cvt_pk_bf16_f32 v111, v111, s0
	global_store_short v[112:113], v111, off
	v_mul_f32_e32 v111, v77, v110
	v_add_co_u32_e32 v126, vcc, s48, v112
	v_cvt_pk_bf16_f32 v111, v111, s0
	s_nop 0
	v_addc_co_u32_e32 v127, vcc, 0, v113, vcc
	global_store_short v[126:127], v111, off offset:512
	v_mul_f32_e32 v111, v74, v110
	v_add_co_u32_e32 v126, vcc, s16, v112
	v_cvt_pk_bf16_f32 v111, v111, s0
	s_nop 0
	v_addc_co_u32_e32 v127, vcc, 0, v113, vcc
	global_store_short v[126:127], v111, off offset:1024
	v_mul_f32_e32 v111, v75, v110
	v_add_co_u32_e32 v126, vcc, s7, v112
	v_cvt_pk_bf16_f32 v111, v111, s0
	s_nop 0
	v_addc_co_u32_e32 v127, vcc, 0, v113, vcc
	global_store_short v[126:127], v111, off offset:1536
	v_mul_f32_e32 v111, v72, v110
	v_lshl_add_u64 v[112:113], v[112:113], 0, s[44:45]
; #define STT(BASE, MUL) { bf16_t* q_ = (BASE) + (size_t)(4 * h) * TOK; _Pragma("unroll") for (int mi = 0; mi < 4; ++mi) _Pragma("unroll") for (int g = 0; g < 4; ++g) { \
;       _Pragma("unroll") for (int e = 0; e < 4; ++e) q_[(size_t)e * TOK] = f2bf(acc[mi][NI][4 * g + e] * (MUL)); q_ += (size_t)8 * TOK; asm volatile("" : "+v"(q_)); } }
; template <int NI> DI void inproj_epi_reg(const Params& p, int layer, int nt, int tok, int h, f32x16 (&acc)[4][2]) {
;     ...
;       STT(KF, df);
;       STT(KB, db);
	v_cvt_pk_bf16_f32 v111, v111, s0
	global_store_short v[112:113], v111, off
	v_mul_f32_e32 v111, v73, v110
	v_add_co_u32_e32 v126, vcc, s48, v112
	v_cvt_pk_bf16_f32 v111, v111, s0
	s_nop 0
	v_addc_co_u32_e32 v127, vcc, 0, v113, vcc
	global_store_short v[126:127], v111, off offset:512
	v_mul_f32_e32 v111, v70, v110
	v_add_co_u32_e32 v126, vcc, s16, v112
	v_cvt_pk_bf16_f32 v111, v111, s0
	s_nop 0
	v_addc_co_u32_e32 v127, vcc, 0, v113, vcc
	global_store_short v[126:127], v111, off offset:1024
	v_mul_f32_e32 v111, v71, v110
	v_add_co_u32_e32 v126, vcc, s7, v112
	v_cvt_pk_bf16_f32 v111, v111, s0
	s_nop 0
	v_addc_co_u32_e32 v127, vcc, 0, v113, vcc
	global_store_short v[126:127], v111, off offset:1536
	v_mul_f32_e32 v111, v68, v110
	v_lshl_add_u64 v[112:113], v[112:113], 0, s[44:45]
	v_cvt_pk_bf16_f32 v111, v111, s0
	global_store_short v[112:113], v111, off
	v_mul_f32_e32 v111, v69, v110
	v_add_co_u32_e32 v126, vcc, s48, v112
	v_cvt_pk_bf16_f32 v111, v111, s0
	s_nop 0
	v_addc_co_u32_e32 v127, vcc, 0, v113, vcc
	global_store_short v[126:127], v111, off offset:512
	v_mul_f32_e32 v111, v66, v110
	v_add_co_u32_e32 v126, vcc, s16, v112
	v_cvt_pk_bf16_f32 v111, v111, s0
	s_nop 0
	v_addc_co_u32_e32 v127, vcc, 0, v113, vcc
	v_mul_f32_e32 v110, v67, v110
	global_store_short v[126:127], v111, off offset:1024
	v_cvt_pk_bf16_f32 v126, v110, s0
	v_add_co_u32_e32 v110, vcc, s7, v112
	v_lshl_add_u64 v[106:107], v[108:109], 0, v[106:107]
	s_nop 0
	v_addc_co_u32_e32 v111, vcc, 0, v113, vcc
	global_store_short v[110:111], v126, off offset:1536
	v_lshl_add_u64 v[110:111], v[112:113], 0, s[44:45]
	v_lshl_add_u64 v[106:107], v[106:107], 0, v[180:181]
	v_exp_f32_e32 v110, v156
	s_nop 0
	v_mul_f32_e32 v108, v146, v110
	v_cvt_pk_bf16_f32 v108, v108, s0
	global_store_short v[106:107], v108, off offset:512
	v_mul_f32_e32 v108, v147, v110
	v_cvt_pk_bf16_f32 v111, v108, s0
	v_add_co_u32_e32 v108, vcc, s48, v106
	v_mul_f32_e32 v104, v104, v110
	s_nop 0
	v_addc_co_u32_e32 v109, vcc, 0, v107, vcc
	global_store_short v[108:109], v111, off offset:1024
	v_mul_f32_e32 v108, v142, v110
	v_cvt_pk_bf16_f32 v111, v108, s0
	v_add_co_u32_e32 v108, vcc, s16, v106
	v_cvt_pk_bf16_f32 v104, v104, s0
	s_nop 0
	v_addc_co_u32_e32 v109, vcc, 0, v107, vcc
	global_store_short v[108:109], v111, off offset:1536
	v_mul_f32_e32 v108, v143, v110
	v_cvt_pk_bf16_f32 v111, v108, s0
	v_add_co_u32_e32 v108, vcc, s7, v106
	v_mul_f32_e32 v102, v102, v110
	s_nop 0
	v_addc_co_u32_e32 v109, vcc, 0, v107, vcc
	global_store_short v[108:109], v111, off offset:2048
	v_mul_f32_e32 v108, v140, v110
	v_lshl_add_u64 v[106:107], v[106:107], 0, s[18:19]
	v_cvt_pk_bf16_f32 v108, v108, s0
	global_store_short v[106:107], v108, off
	v_mul_f32_e32 v108, v141, v110
	v_cvt_pk_bf16_f32 v111, v108, s0
	v_add_co_u32_e32 v108, vcc, s48, v106
	v_cvt_pk_bf16_f32 v102, v102, s0
	s_nop 0
	v_addc_co_u32_e32 v109, vcc, 0, v107, vcc
	global_store_short v[108:109], v111, off offset:512
	v_mul_f32_e32 v108, v138, v110
	v_cvt_pk_bf16_f32 v111, v108, s0
	v_add_co_u32_e32 v108, vcc, s16, v106
	v_mul_f32_e32 v100, v100, v110
	s_nop 0
	v_addc_co_u32_e32 v109, vcc, 0, v107, vcc
	global_store_short v[108:109], v111, off offset:1024
	v_mul_f32_e32 v108, v139, v110
	v_cvt_pk_bf16_f32 v111, v108, s0
	v_add_co_u32_e32 v108, vcc, s7, v106
	v_cvt_pk_bf16_f32 v100, v100, s0
	s_nop 0
	v_addc_co_u32_e32 v109, vcc, 0, v107, vcc
	global_store_short v[108:109], v111, off offset:1536
	v_mul_f32_e32 v108, v136, v110
	v_lshl_add_u64 v[106:107], v[106:107], 0, s[44:45]
	v_cvt_pk_bf16_f32 v108, v108, s0
	global_store_short v[106:107], v108, off
	v_mul_f32_e32 v108, v137, v110
	v_cvt_pk_bf16_f32 v111, v108, s0
	v_add_co_u32_e32 v108, vcc, s48, v106
	v_mul_f32_e32 v98, v98, v110
	s_nop 0
	v_addc_co_u32_e32 v109, vcc, 0, v107, vcc
	global_store_short v[108:109], v111, off offset:512
	v_mul_f32_e32 v108, v134, v110
	v_cvt_pk_bf16_f32 v111, v108, s0
	v_add_co_u32_e32 v108, vcc, s16, v106
	v_cvt_pk_bf16_f32 v98, v98, s0
	s_nop 0
	v_addc_co_u32_e32 v109, vcc, 0, v107, vcc
	global_store_short v[108:109], v111, off offset:1024
	v_mul_f32_e32 v108, v135, v110
	v_cvt_pk_bf16_f32 v111, v108, s0
	v_add_co_u32_e32 v108, vcc, s7, v106
	v_mul_f32_e32 v96, v96, v110
	s_nop 0
	v_addc_co_u32_e32 v109, vcc, 0, v107, vcc
	global_store_short v[108:109], v111, off offset:1536
	v_mul_f32_e32 v108, v124, v110
	v_lshl_add_u64 v[106:107], v[106:107], 0, s[44:45]
	v_cvt_pk_bf16_f32 v108, v108, s0
	global_store_short v[106:107], v108, off
	v_mul_f32_e32 v108, v125, v110
	v_cvt_pk_bf16_f32 v111, v108, s0
	v_add_co_u32_e32 v108, vcc, s48, v106
	v_cvt_pk_bf16_f32 v96, v96, s0
	s_nop 0
	v_addc_co_u32_e32 v109, vcc, 0, v107, vcc
	global_store_short v[108:109], v111, off offset:512
	v_mul_f32_e32 v108, v122, v110
	v_cvt_pk_bf16_f32 v111, v108, s0
	v_add_co_u32_e32 v108, vcc, s16, v106
	v_mul_f32_e32 v94, v94, v110
	s_nop 0
	v_addc_co_u32_e32 v109, vcc, 0, v107, vcc
	global_store_short v[108:109], v111, off offset:1024
	v_mul_f32_e32 v108, v123, v110
	v_cvt_pk_bf16_f32 v111, v108, s0
	v_add_co_u32_e32 v108, vcc, s7, v106
	v_cvt_pk_bf16_f32 v94, v94, s0
	s_nop 0
	v_addc_co_u32_e32 v109, vcc, 0, v107, vcc
	global_store_short v[108:109], v111, off offset:1536
	v_mul_f32_e32 v108, v120, v110
	v_lshl_add_u64 v[106:107], v[106:107], 0, s[44:45]
	v_cvt_pk_bf16_f32 v108, v108, s0
	global_store_short v[106:107], v108, off
	v_mul_f32_e32 v108, v121, v110
	v_cvt_pk_bf16_f32 v111, v108, s0
	v_add_co_u32_e32 v108, vcc, s48, v106
	v_mul_f32_e32 v92, v92, v110
	s_nop 0
	v_addc_co_u32_e32 v109, vcc, 0, v107, vcc
	global_store_short v[108:109], v111, off offset:512
	v_mul_f32_e32 v108, v118, v110
; #define STT(BASE, MUL) { bf16_t* q_ = (BASE) + (size_t)(4 * h) * TOK; _Pragma("unroll") for (int mi = 0; mi < 4; ++mi) _Pragma("unroll") for (int g = 0; g < 4; ++g) { \
;       _Pragma("unroll") for (int e = 0; e < 4; ++e) q_[(size_t)e * TOK] = f2bf(acc[mi][NI][4 * g + e] * (MUL)); q_ += (size_t)8 * TOK; asm volatile("" : "+v"(q_)); } }
; template <int NI> DI void inproj_epi_reg(const Params& p, int layer, int nt, int tok, int h, f32x16 (&acc)[4][2]) {
;     ...
;       STT(KB, db);
	v_cvt_pk_bf16_f32 v111, v108, s0
	v_add_co_u32_e32 v108, vcc, s16, v106
	v_cvt_pk_bf16_f32 v92, v92, s0
	s_nop 0
	v_addc_co_u32_e32 v109, vcc, 0, v107, vcc
	global_store_short v[108:109], v111, off offset:1024
	v_mul_f32_e32 v108, v119, v110
	v_cvt_pk_bf16_f32 v111, v108, s0
	v_add_co_u32_e32 v108, vcc, s7, v106
	v_mul_f32_e32 v90, v90, v110
	s_nop 0
	v_addc_co_u32_e32 v109, vcc, 0, v107, vcc
	global_store_short v[108:109], v111, off offset:1536
	v_mul_f32_e32 v108, v116, v110
	v_lshl_add_u64 v[106:107], v[106:107], 0, s[44:45]
	v_cvt_pk_bf16_f32 v108, v108, s0
	global_store_short v[106:107], v108, off
	v_mul_f32_e32 v108, v117, v110
	v_cvt_pk_bf16_f32 v111, v108, s0
	v_add_co_u32_e32 v108, vcc, s48, v106
	v_cvt_pk_bf16_f32 v90, v90, s0
	s_nop 0
	v_addc_co_u32_e32 v109, vcc, 0, v107, vcc
	global_store_short v[108:109], v111, off offset:512
	v_mul_f32_e32 v108, v114, v110
	v_cvt_pk_bf16_f32 v111, v108, s0
	v_add_co_u32_e32 v108, vcc, s16, v106
	v_mul_f32_e32 v88, v88, v110
	s_nop 0
	v_addc_co_u32_e32 v109, vcc, 0, v107, vcc
	global_store_short v[108:109], v111, off offset:1024
	v_mul_f32_e32 v108, v115, v110
	v_cvt_pk_bf16_f32 v111, v108, s0
	v_add_co_u32_e32 v108, vcc, s7, v106
	v_cvt_pk_bf16_f32 v88, v88, s0
	s_nop 0
	v_addc_co_u32_e32 v109, vcc, 0, v107, vcc
	v_lshl_add_u64 v[106:107], v[106:107], 0, s[44:45]
	global_store_short v[108:109], v111, off offset:1536
	global_store_short v[106:107], v104, off
	v_mul_f32_e32 v104, v105, v110
	v_cvt_pk_bf16_f32 v108, v104, s0
	v_add_co_u32_e32 v104, vcc, s48, v106
	v_mul_f32_e32 v86, v86, v110
	s_nop 0
	v_addc_co_u32_e32 v105, vcc, 0, v107, vcc
	global_store_short v[104:105], v108, off offset:512
	v_add_co_u32_e32 v104, vcc, s16, v106
	v_cvt_pk_bf16_f32 v86, v86, s0
	s_nop 0
	v_addc_co_u32_e32 v105, vcc, 0, v107, vcc
	global_store_short v[104:105], v102, off offset:1024
	v_mul_f32_e32 v102, v103, v110
	v_cvt_pk_bf16_f32 v104, v102, s0
	v_add_co_u32_e32 v102, vcc, s7, v106
	v_mul_f32_e32 v84, v84, v110
	s_nop 0
	v_addc_co_u32_e32 v103, vcc, 0, v107, vcc
	global_store_short v[102:103], v104, off offset:1536
	v_lshl_add_u64 v[102:103], v[106:107], 0, s[44:45]
	global_store_short v[102:103], v100, off
	v_mul_f32_e32 v100, v101, v110
	v_cvt_pk_bf16_f32 v104, v100, s0
	v_add_co_u32_e32 v100, vcc, s48, v102
	v_cvt_pk_bf16_f32 v84, v84, s0
	s_nop 0
	v_addc_co_u32_e32 v101, vcc, 0, v103, vcc
	global_store_short v[100:101], v104, off offset:512
	v_add_co_u32_e32 v100, vcc, s16, v102
	v_mul_f32_e32 v82, v82, v110
	s_nop 0
	v_addc_co_u32_e32 v101, vcc, 0, v103, vcc
	global_store_short v[100:101], v98, off offset:1024
	v_mul_f32_e32 v98, v99, v110
	v_cvt_pk_bf16_f32 v100, v98, s0
	v_add_co_u32_e32 v98, vcc, s7, v102
	v_cvt_pk_bf16_f32 v82, v82, s0
	s_nop 0
	v_addc_co_u32_e32 v99, vcc, 0, v103, vcc
	global_store_short v[98:99], v100, off offset:1536
	v_lshl_add_u64 v[98:99], v[102:103], 0, s[44:45]
	global_store_short v[98:99], v96, off
	v_mul_f32_e32 v96, v97, v110
	v_cvt_pk_bf16_f32 v100, v96, s0
	v_add_co_u32_e32 v96, vcc, s48, v98
	v_mul_f32_e32 v80, v80, v110
	s_nop 0
	v_addc_co_u32_e32 v97, vcc, 0, v99, vcc
	global_store_short v[96:97], v100, off offset:512
	v_add_co_u32_e32 v96, vcc, s16, v98
	v_cvt_pk_bf16_f32 v80, v80, s0
	s_nop 0
	v_addc_co_u32_e32 v97, vcc, 0, v99, vcc
	global_store_short v[96:97], v94, off offset:1024
	v_mul_f32_e32 v94, v95, v110
	v_cvt_pk_bf16_f32 v96, v94, s0
	v_add_co_u32_e32 v94, vcc, s7, v98
	v_mul_f32_e32 v78, v78, v110
	s_nop 0
	v_addc_co_u32_e32 v95, vcc, 0, v99, vcc
	global_store_short v[94:95], v96, off offset:1536
	v_lshl_add_u64 v[94:95], v[98:99], 0, s[44:45]
	global_store_short v[94:95], v92, off
	v_mul_f32_e32 v92, v93, v110
	v_cvt_pk_bf16_f32 v96, v92, s0
	v_add_co_u32_e32 v92, vcc, s48, v94
	v_cvt_pk_bf16_f32 v78, v78, s0
	s_nop 0
	v_addc_co_u32_e32 v93, vcc, 0, v95, vcc
	global_store_short v[92:93], v96, off offset:512
	v_add_co_u32_e32 v92, vcc, s16, v94
	v_mul_f32_e32 v76, v76, v110
	s_nop 0
	v_addc_co_u32_e32 v93, vcc, 0, v95, vcc
	global_store_short v[92:93], v90, off offset:1024
	v_mul_f32_e32 v90, v91, v110
	v_cvt_pk_bf16_f32 v92, v90, s0
	v_add_co_u32_e32 v90, vcc, s7, v94
	v_cvt_pk_bf16_f32 v76, v76, s0
	s_nop 0
; #define STT(BASE, MUL) { bf16_t* q_ = (BASE) + (size_t)(4 * h) * TOK; _Pragma("unroll") for (int mi = 0; mi < 4; ++mi) _Pragma("unroll") for (int g = 0; g < 4; ++g) { \
;       _Pragma("unroll") for (int e = 0; e < 4; ++e) q_[(size_t)e * TOK] = f2bf(acc[mi][NI][4 * g + e] * (MUL)); q_ += (size_t)8 * TOK; asm volatile("" : "+v"(q_)); } }
; template <int NI> DI void inproj_epi_reg(const Params& p, int layer, int nt, int tok, int h, f32x16 (&acc)[4][2]) {
;     ...
;       bf16_t* KF = (bf16_t*)(p.ws + O_RKTF) + (size_t)(hd * 128) * TOK + tok;
;       bf16_t* KB = (bf16_t*)(p.ws + O_RKTB) + (size_t)(hd * 128) * TOK + tok;
;       STT(KF, df);
;       STT(KB, db);
	v_addc_co_u32_e32 v91, vcc, 0, v95, vcc
	global_store_short v[90:91], v92, off offset:1536
	v_lshl_add_u64 v[90:91], v[94:95], 0, s[44:45]
	global_store_short v[90:91], v88, off
	v_mul_f32_e32 v88, v89, v110
	v_cvt_pk_bf16_f32 v92, v88, s0
	v_add_co_u32_e32 v88, vcc, s48, v90
	v_mul_f32_e32 v74, v74, v110
	s_nop 0
	v_addc_co_u32_e32 v89, vcc, 0, v91, vcc
	global_store_short v[88:89], v92, off offset:512
	v_add_co_u32_e32 v88, vcc, s16, v90
	v_cvt_pk_bf16_f32 v74, v74, s0
	s_nop 0
	v_addc_co_u32_e32 v89, vcc, 0, v91, vcc
	global_store_short v[88:89], v86, off offset:1024
	v_mul_f32_e32 v86, v87, v110
	v_cvt_pk_bf16_f32 v88, v86, s0
	v_add_co_u32_e32 v86, vcc, s7, v90
	v_mul_f32_e32 v72, v72, v110
	s_nop 0
	v_addc_co_u32_e32 v87, vcc, 0, v91, vcc
	global_store_short v[86:87], v88, off offset:1536
	v_lshl_add_u64 v[86:87], v[90:91], 0, s[44:45]
	global_store_short v[86:87], v84, off
	v_mul_f32_e32 v84, v85, v110
	v_cvt_pk_bf16_f32 v88, v84, s0
	v_add_co_u32_e32 v84, vcc, s48, v86
	v_cvt_pk_bf16_f32 v72, v72, s0
	s_nop 0
	v_addc_co_u32_e32 v85, vcc, 0, v87, vcc
	global_store_short v[84:85], v88, off offset:512
	v_add_co_u32_e32 v84, vcc, s16, v86
	v_mul_f32_e32 v70, v70, v110
	s_nop 0
	v_addc_co_u32_e32 v85, vcc, 0, v87, vcc
	global_store_short v[84:85], v82, off offset:1024
	v_mul_f32_e32 v82, v83, v110
	v_cvt_pk_bf16_f32 v84, v82, s0
	v_add_co_u32_e32 v82, vcc, s7, v86
	v_cvt_pk_bf16_f32 v70, v70, s0
	s_nop 0
	v_addc_co_u32_e32 v83, vcc, 0, v87, vcc
	global_store_short v[82:83], v84, off offset:1536
	v_lshl_add_u64 v[82:83], v[86:87], 0, s[44:45]
	global_store_short v[82:83], v80, off
	v_mul_f32_e32 v80, v81, v110
	v_cvt_pk_bf16_f32 v84, v80, s0
	v_add_co_u32_e32 v80, vcc, s48, v82
	v_mul_f32_e32 v68, v68, v110
	s_nop 0
	v_addc_co_u32_e32 v81, vcc, 0, v83, vcc
	global_store_short v[80:81], v84, off offset:512
	v_add_co_u32_e32 v80, vcc, s16, v82
	v_cvt_pk_bf16_f32 v68, v68, s0
	s_nop 0
	v_addc_co_u32_e32 v81, vcc, 0, v83, vcc
	global_store_short v[80:81], v78, off offset:1024
	v_mul_f32_e32 v78, v79, v110
	v_cvt_pk_bf16_f32 v80, v78, s0
	v_add_co_u32_e32 v78, vcc, s7, v82
	v_mul_f32_e32 v66, v66, v110
	s_nop 0
	v_addc_co_u32_e32 v79, vcc, 0, v83, vcc
	global_store_short v[78:79], v80, off offset:1536
	v_lshl_add_u64 v[78:79], v[82:83], 0, s[44:45]
	global_store_short v[78:79], v76, off
	v_mul_f32_e32 v76, v77, v110
	v_cvt_pk_bf16_f32 v80, v76, s0
	v_add_co_u32_e32 v76, vcc, s48, v78
	v_cvt_pk_bf16_f32 v66, v66, s0
	s_nop 0
	v_addc_co_u32_e32 v77, vcc, 0, v79, vcc
	global_store_short v[76:77], v80, off offset:512
	v_add_co_u32_e32 v76, vcc, s16, v78
	s_nop 1
	v_addc_co_u32_e32 v77, vcc, 0, v79, vcc
	global_store_short v[76:77], v74, off offset:1024
	v_mul_f32_e32 v74, v75, v110
	v_cvt_pk_bf16_f32 v76, v74, s0
	v_add_co_u32_e32 v74, vcc, s7, v78
	s_nop 1
	v_addc_co_u32_e32 v75, vcc, 0, v79, vcc
	global_store_short v[74:75], v76, off offset:1536
	v_lshl_add_u64 v[74:75], v[78:79], 0, s[44:45]
	global_store_short v[74:75], v72, off
	v_mul_f32_e32 v72, v73, v110
	v_cvt_pk_bf16_f32 v76, v72, s0
	v_add_co_u32_e32 v72, vcc, s48, v74
	s_nop 1
	v_addc_co_u32_e32 v73, vcc, 0, v75, vcc
	global_store_short v[72:73], v76, off offset:512
	v_add_co_u32_e32 v72, vcc, s16, v74
	s_nop 1
	v_addc_co_u32_e32 v73, vcc, 0, v75, vcc
	global_store_short v[72:73], v70, off offset:1024
	v_mul_f32_e32 v70, v71, v110
	v_cvt_pk_bf16_f32 v72, v70, s0
	v_add_co_u32_e32 v70, vcc, s7, v74
	s_nop 1
	v_addc_co_u32_e32 v71, vcc, 0, v75, vcc
	global_store_short v[70:71], v72, off offset:1536
	v_lshl_add_u64 v[70:71], v[74:75], 0, s[44:45]
	global_store_short v[70:71], v68, off
	v_mul_f32_e32 v68, v69, v110
	v_cvt_pk_bf16_f32 v72, v68, s0
	v_add_co_u32_e32 v68, vcc, 0x4000, v70
	s_nop 1
	v_addc_co_u32_e32 v69, vcc, 0, v71, vcc
	global_store_short v[68:69], v72, off offset:512
	v_add_co_u32_e32 v68, vcc, 0x8000, v70
	s_nop 1
	v_addc_co_u32_e32 v69, vcc, 0, v71, vcc
	global_store_short v[68:69], v66, off offset:1024
	v_mul_f32_e32 v66, v67, v110
	v_cvt_pk_bf16_f32 v68, v66, s0
	v_add_co_u32_e32 v66, vcc, 0xc000, v70
	s_nop 1
	v_addc_co_u32_e32 v67, vcc, 0, v71, vcc
	global_store_short v[66:67], v68, off offset:1536
	v_lshl_add_u64 v[66:67], v[70:71], 0, s[44:45]

; #define STT(BASE, MUL) { bf16_t* q_ = (BASE) + (size_t)(4 * h) * TOK; _Pragma("unroll") for (int mi = 0; mi < 4; ++mi) _Pragma("unroll") for (int g = 0; g < 4; ++g) { \
;       _Pragma("unroll") for (int e = 0; e < 4; ++e) q_[(size_t)e * TOK] = f2bf(acc[mi][NI][4 * g + e] * (MUL)); q_ += (size_t)8 * TOK; asm volatile("" : "+v"(q_)); } }
; template <int NI> DI void inproj_epi_reg(const Params& p, int layer, int nt, int tok, int h, f32x16 (&acc)[4][2]) {
;     ...
;   } else {
;     bf16_t* VT = (bf16_t*)(p.ws + O_DVT) + (size_t)((nt - 40) * 128) * TOK + tok;
;     STT(VT, 1.f);
.LBB0_223:
	s_or_b64 exec, exec, s[8:9]
	v_or_b32_e32 v66, 32, v130
	s_and_saveexec_b64 s[8:9], s[42:43]
	s_xor_b64 s[8:9], exec, s[8:9]
	s_cbranch_execz .LBB0_249
	v_cmp_lt_u32_e32 vcc, 7, v237
	s_and_saveexec_b64 s[10:11], vcc
	s_xor_b64 s[10:11], exec, s[10:11]
	s_cbranch_execz .LBB0_246
	v_add_u32_e32 v67, 0x1f20, v130
	v_bfe_u32 v72, v67, 6, 7
	v_and_b32_e32 v67, 63, v66
	v_cmp_lt_u32_e32 vcc, 15, v237
	s_and_saveexec_b64 s[12:13], vcc
	s_xor_b64 s[12:13], exec, s[12:13]
	s_cbranch_execz .LBB0_239
	v_cmp_lt_u32_e32 vcc, 19, v237
	s_and_saveexec_b64 s[14:15], vcc
	s_xor_b64 s[14:15], exec, s[14:15]
	s_cbranch_execz .LBB0_236
	v_cmp_lt_u32_e32 vcc, 23, v237
	s_and_saveexec_b64 s[16:17], vcc
	s_xor_b64 s[16:17], exec, s[16:17]
	s_cbranch_execz .LBB0_233
	v_cmp_lt_u32_e32 vcc, 39, v237
	s_and_saveexec_b64 s[18:19], vcc
	s_xor_b64 s[18:19], exec, s[18:19]
	s_cbranch_execz .LBB0_230
	v_readlane_b32 s42, v253, 54
	v_mov_b32_e32 v66, 0xffffec00
	v_readlane_b32 s43, v253, 55
	v_lshl_add_u32 v68, v237, 7, v66
	v_mov_b32_e32 v133, v181
	v_mov_b64_e32 v[66:67], s[42:43]
	s_ashr_i32 s7, s6, 31
	v_mad_u64_u32 v[66:67], s[42:43], v68, s29, v[66:67]
	v_lshl_add_u64 v[68:69], v[132:133], 0, s[6:7]
	v_lshl_add_u64 v[66:67], v[68:69], 1, v[66:67]
	v_mul_u32_u24_e32 v68, 0x8400, v193
	v_lshlrev_b32_e32 v180, 1, v68
	v_lshl_add_u64 v[66:67], v[66:67], 0, v[180:181]
	v_cvt_pk_bf16_f32 v50, v50, s0
	global_store_short v[66:67], v50, off offset:576
	v_add_co_u32_e32 v50, vcc, s48, v66
	v_cvt_pk_bf16_f32 v68, v51, s0
	s_nop 0
	v_addc_co_u32_e32 v51, vcc, 0, v67, vcc
	s_mov_b32 s42, 0x8000
	global_store_short v[50:51], v68, off offset:1088
	v_add_co_u32_e32 v50, vcc, s42, v66
	v_cvt_pk_bf16_f32 v52, v52, s0
	s_nop 0
	v_addc_co_u32_e32 v51, vcc, 0, v67, vcc
	s_mov_b32 s7, 0xc000
	global_store_short v[50:51], v52, off offset:1600
	v_add_co_u32_e32 v50, vcc, s7, v66
	v_cvt_pk_bf16_f32 v52, v53, s0
	s_nop 0
	v_addc_co_u32_e32 v51, vcc, 0, v67, vcc
	s_mov_b64 s[44:45], 0x21240
	global_store_short v[50:51], v52, off offset:2112
	v_lshl_add_u64 v[50:51], v[66:67], 0, s[44:45]
	v_cvt_pk_bf16_f32 v52, v54, s0
	global_store_short v[50:51], v52, off
	v_add_co_u32_e32 v52, vcc, s48, v50
	v_cvt_pk_bf16_f32 v54, v55, s0
	s_nop 0
	v_addc_co_u32_e32 v53, vcc, 0, v51, vcc
	global_store_short v[52:53], v54, off offset:512
	v_add_co_u32_e32 v52, vcc, s42, v50
	v_cvt_pk_bf16_f32 v54, v56, s0
	s_nop 0
	v_addc_co_u32_e32 v53, vcc, 0, v51, vcc
	global_store_short v[52:53], v54, off offset:1024
	v_add_co_u32_e32 v52, vcc, s7, v50
	v_cvt_pk_bf16_f32 v54, v57, s0
	s_nop 0
	v_addc_co_u32_e32 v53, vcc, 0, v51, vcc
	s_mov_b64 s[44:45], 0x21000
	global_store_short v[52:53], v54, off offset:1536
	v_lshl_add_u64 v[50:51], v[50:51], 0, s[44:45]
	v_cvt_pk_bf16_f32 v52, v58, s0
	global_store_short v[50:51], v52, off
	v_add_co_u32_e32 v52, vcc, s48, v50
	v_cvt_pk_bf16_f32 v54, v59, s0
	s_nop 0
	v_addc_co_u32_e32 v53, vcc, 0, v51, vcc
	global_store_short v[52:53], v54, off offset:512
	v_add_co_u32_e32 v52, vcc, s42, v50
	v_cvt_pk_bf16_f32 v54, v60, s0
	s_nop 0
	v_addc_co_u32_e32 v53, vcc, 0, v51, vcc
	global_store_short v[52:53], v54, off offset:1024
	v_add_co_u32_e32 v52, vcc, s7, v50
	v_cvt_pk_bf16_f32 v54, v61, s0
	s_nop 0
	v_addc_co_u32_e32 v53, vcc, 0, v51, vcc
	global_store_short v[52:53], v54, off offset:1536
	v_lshl_add_u64 v[50:51], v[50:51], 0, s[44:45]
	v_cvt_pk_bf16_f32 v52, v62, s0
	global_store_short v[50:51], v52, off
	v_add_co_u32_e32 v52, vcc, s48, v50
	v_cvt_pk_bf16_f32 v54, v63, s0
	s_nop 0
	v_addc_co_u32_e32 v53, vcc, 0, v51, vcc
	global_store_short v[52:53], v54, off offset:512
	v_add_co_u32_e32 v52, vcc, s42, v50
	v_cvt_pk_bf16_f32 v54, v64, s0
	s_nop 0
	v_addc_co_u32_e32 v53, vcc, 0, v51, vcc
	global_store_short v[52:53], v54, off offset:1024
	v_add_co_u32_e32 v52, vcc, s7, v50
	v_cvt_pk_bf16_f32 v54, v65, s0
	s_nop 0
	v_addc_co_u32_e32 v53, vcc, 0, v51, vcc
	v_lshl_add_u64 v[50:51], v[50:51], 0, s[44:45]
	v_cvt_pk_bf16_f32 v34, v34, s0
	global_store_short v[52:53], v54, off offset:1536
	global_store_short v[50:51], v34, off
	v_add_co_u32_e32 v34, vcc, s48, v50
	v_cvt_pk_bf16_f32 v52, v35, s0
	s_nop 0
	v_addc_co_u32_e32 v35, vcc, 0, v51, vcc
	global_store_short v[34:35], v52, off offset:512
	v_add_co_u32_e32 v34, vcc, s42, v50
	v_cvt_pk_bf16_f32 v36, v36, s0
	s_nop 0
	v_addc_co_u32_e32 v35, vcc, 0, v51, vcc
	global_store_short v[34:35], v36, off offset:1024
	v_add_co_u32_e32 v34, vcc, s7, v50
	v_cvt_pk_bf16_f32 v36, v37, s0
	s_nop 0
	v_addc_co_u32_e32 v35, vcc, 0, v51, vcc
	global_store_short v[34:35], v36, off offset:1536
	v_lshl_add_u64 v[34:35], v[50:51], 0, s[44:45]
	v_cvt_pk_bf16_f32 v36, v38, s0
	global_store_short v[34:35], v36, off
	v_add_co_u32_e32 v36, vcc, s48, v34
	v_cvt_pk_bf16_f32 v38, v39, s0
	s_nop 0
	v_addc_co_u32_e32 v37, vcc, 0, v35, vcc
	global_store_short v[36:37], v38, off offset:512
	v_add_co_u32_e32 v36, vcc, s42, v34
	v_cvt_pk_bf16_f32 v38, v40, s0
	s_nop 0
	v_addc_co_u32_e32 v37, vcc, 0, v35, vcc
	global_store_short v[36:37], v38, off offset:1024
	v_add_co_u32_e32 v36, vcc, s7, v34
	v_cvt_pk_bf16_f32 v38, v41, s0
	s_nop 0
	v_addc_co_u32_e32 v37, vcc, 0, v35, vcc
	global_store_short v[36:37], v38, off offset:1536
	v_lshl_add_u64 v[34:35], v[34:35], 0, s[44:45]
	v_cvt_pk_bf16_f32 v36, v42, s0
	global_store_short v[34:35], v36, off
	v_add_co_u32_e32 v36, vcc, s48, v34
	v_cvt_pk_bf16_f32 v38, v43, s0
	s_nop 0
	v_addc_co_u32_e32 v37, vcc, 0, v35, vcc
	global_store_short v[36:37], v38, off offset:512
	v_add_co_u32_e32 v36, vcc, s42, v34
	v_cvt_pk_bf16_f32 v38, v44, s0
	s_nop 0
	v_addc_co_u32_e32 v37, vcc, 0, v35, vcc
	global_store_short v[36:37], v38, off offset:1024
; #define STT(BASE, MUL) { bf16_t* q_ = (BASE) + (size_t)(4 * h) * TOK; _Pragma("unroll") for (int mi = 0; mi < 4; ++mi) _Pragma("unroll") for (int g = 0; g < 4; ++g) { \
;       _Pragma("unroll") for (int e = 0; e < 4; ++e) q_[(size_t)e * TOK] = f2bf(acc[mi][NI][4 * g + e] * (MUL)); q_ += (size_t)8 * TOK; asm volatile("" : "+v"(q_)); } }
; template <int NI> DI void inproj_epi_reg(const Params& p, int layer, int nt, int tok, int h, f32x16 (&acc)[4][2]) {
;     ...
;   } else {
;     bf16_t* VT = (bf16_t*)(p.ws + O_DVT) + (size_t)((nt - 40) * 128) * TOK + tok;
;     STT(VT, 1.f);
	v_add_co_u32_e32 v36, vcc, s7, v34
	v_cvt_pk_bf16_f32 v38, v45, s0
	s_nop 0
	v_addc_co_u32_e32 v37, vcc, 0, v35, vcc
	global_store_short v[36:37], v38, off offset:1536
	v_lshl_add_u64 v[34:35], v[34:35], 0, s[44:45]
	v_cvt_pk_bf16_f32 v36, v46, s0
	global_store_short v[34:35], v36, off
	v_add_co_u32_e32 v36, vcc, s48, v34
	v_cvt_pk_bf16_f32 v38, v47, s0
	s_nop 0
	v_addc_co_u32_e32 v37, vcc, 0, v35, vcc
	global_store_short v[36:37], v38, off offset:512
	v_add_co_u32_e32 v36, vcc, s42, v34
	v_cvt_pk_bf16_f32 v38, v48, s0
	s_nop 0
	v_addc_co_u32_e32 v37, vcc, 0, v35, vcc
	global_store_short v[36:37], v38, off offset:1024
	v_add_co_u32_e32 v36, vcc, s7, v34
	v_cvt_pk_bf16_f32 v38, v49, s0
	s_nop 0
	v_addc_co_u32_e32 v37, vcc, 0, v35, vcc
	v_lshl_add_u64 v[34:35], v[34:35], 0, s[44:45]
	v_cvt_pk_bf16_f32 v18, v18, s0
	global_store_short v[36:37], v38, off offset:1536
	global_store_short v[34:35], v18, off
	v_add_co_u32_e32 v18, vcc, s48, v34
	v_cvt_pk_bf16_f32 v36, v19, s0
	s_nop 0
	v_addc_co_u32_e32 v19, vcc, 0, v35, vcc
	global_store_short v[18:19], v36, off offset:512
	v_add_co_u32_e32 v18, vcc, s42, v34
	v_cvt_pk_bf16_f32 v20, v20, s0
	s_nop 0
	v_addc_co_u32_e32 v19, vcc, 0, v35, vcc
	global_store_short v[18:19], v20, off offset:1024
	v_add_co_u32_e32 v18, vcc, s7, v34
	v_cvt_pk_bf16_f32 v20, v21, s0
	s_nop 0
	v_addc_co_u32_e32 v19, vcc, 0, v35, vcc
	global_store_short v[18:19], v20, off offset:1536
	v_lshl_add_u64 v[18:19], v[34:35], 0, s[44:45]
	v_cvt_pk_bf16_f32 v20, v22, s0
	global_store_short v[18:19], v20, off
	v_add_co_u32_e32 v20, vcc, s48, v18
	v_cvt_pk_bf16_f32 v22, v23, s0
	s_nop 0
	v_addc_co_u32_e32 v21, vcc, 0, v19, vcc
	global_store_short v[20:21], v22, off offset:512
	v_add_co_u32_e32 v20, vcc, s42, v18
	v_cvt_pk_bf16_f32 v22, v24, s0
	s_nop 0
	v_addc_co_u32_e32 v21, vcc, 0, v19, vcc
	global_store_short v[20:21], v22, off offset:1024
	v_add_co_u32_e32 v20, vcc, s7, v18
	v_cvt_pk_bf16_f32 v22, v25, s0
	s_nop 0
	v_addc_co_u32_e32 v21, vcc, 0, v19, vcc
	global_store_short v[20:21], v22, off offset:1536
	v_lshl_add_u64 v[18:19], v[18:19], 0, s[44:45]
	v_cvt_pk_bf16_f32 v20, v26, s0
	global_store_short v[18:19], v20, off
	v_add_co_u32_e32 v20, vcc, s48, v18
	v_cvt_pk_bf16_f32 v22, v27, s0
	s_nop 0
	v_addc_co_u32_e32 v21, vcc, 0, v19, vcc
	global_store_short v[20:21], v22, off offset:512
	v_add_co_u32_e32 v20, vcc, s42, v18
	v_cvt_pk_bf16_f32 v22, v28, s0
	s_nop 0
	v_addc_co_u32_e32 v21, vcc, 0, v19, vcc
	global_store_short v[20:21], v22, off offset:1024
	v_add_co_u32_e32 v20, vcc, s7, v18
	v_cvt_pk_bf16_f32 v22, v29, s0
	s_nop 0
	v_addc_co_u32_e32 v21, vcc, 0, v19, vcc
	global_store_short v[20:21], v22, off offset:1536
	v_lshl_add_u64 v[18:19], v[18:19], 0, s[44:45]
	v_cvt_pk_bf16_f32 v20, v30, s0
	global_store_short v[18:19], v20, off
	v_add_co_u32_e32 v20, vcc, s48, v18
	v_cvt_pk_bf16_f32 v22, v31, s0
	s_nop 0
	v_addc_co_u32_e32 v21, vcc, 0, v19, vcc
	global_store_short v[20:21], v22, off offset:512
	v_add_co_u32_e32 v20, vcc, s42, v18
	v_cvt_pk_bf16_f32 v22, v32, s0
	s_nop 0
	v_addc_co_u32_e32 v21, vcc, 0, v19, vcc
	global_store_short v[20:21], v22, off offset:1024
	v_add_co_u32_e32 v20, vcc, s7, v18
	v_cvt_pk_bf16_f32 v22, v33, s0
	s_nop 0
	v_addc_co_u32_e32 v21, vcc, 0, v19, vcc
	v_lshl_add_u64 v[18:19], v[18:19], 0, s[44:45]
	v_cvt_pk_bf16_f32 v2, v2, s0
	global_store_short v[20:21], v22, off offset:1536
	global_store_short v[18:19], v2, off
	v_add_co_u32_e32 v2, vcc, s48, v18
	v_cvt_pk_bf16_f32 v20, v3, s0
	s_nop 0
	v_addc_co_u32_e32 v3, vcc, 0, v19, vcc
	global_store_short v[2:3], v20, off offset:512
	v_add_co_u32_e32 v2, vcc, s42, v18
	v_cvt_pk_bf16_f32 v4, v4, s0
	s_nop 0
	v_addc_co_u32_e32 v3, vcc, 0, v19, vcc
	global_store_short v[2:3], v4, off offset:1024
	v_add_co_u32_e32 v2, vcc, s7, v18
	v_cvt_pk_bf16_f32 v4, v5, s0
	s_nop 0
	v_addc_co_u32_e32 v3, vcc, 0, v19, vcc
	global_store_short v[2:3], v4, off offset:1536
	v_lshl_add_u64 v[2:3], v[18:19], 0, s[44:45]
	v_cvt_pk_bf16_f32 v4, v6, s0
	global_store_short v[2:3], v4, off
	v_add_co_u32_e32 v4, vcc, s48, v2
	v_cvt_pk_bf16_f32 v6, v7, s0
	s_nop 0
	v_addc_co_u32_e32 v5, vcc, 0, v3, vcc
	global_store_short v[4:5], v6, off offset:512
	v_add_co_u32_e32 v4, vcc, s42, v2
	v_cvt_pk_bf16_f32 v6, v8, s0
	s_nop 0
	v_addc_co_u32_e32 v5, vcc, 0, v3, vcc
	global_store_short v[4:5], v6, off offset:1024
	v_add_co_u32_e32 v4, vcc, s7, v2
	v_cvt_pk_bf16_f32 v6, v9, s0
	s_nop 0
	v_addc_co_u32_e32 v5, vcc, 0, v3, vcc
	global_store_short v[4:5], v6, off offset:1536
	v_lshl_add_u64 v[2:3], v[2:3], 0, s[44:45]
	v_cvt_pk_bf16_f32 v4, v10, s0
	global_store_short v[2:3], v4, off
	v_add_co_u32_e32 v4, vcc, s48, v2
	v_cvt_pk_bf16_f32 v6, v11, s0
	s_nop 0
	v_addc_co_u32_e32 v5, vcc, 0, v3, vcc
	global_store_short v[4:5], v6, off offset:512
	v_add_co_u32_e32 v4, vcc, 0x8000, v2
	v_cvt_pk_bf16_f32 v6, v12, s0
	s_nop 0
	v_addc_co_u32_e32 v5, vcc, 0, v3, vcc
	global_store_short v[4:5], v6, off offset:1024
	v_add_co_u32_e32 v4, vcc, s7, v2
	v_cvt_pk_bf16_f32 v6, v13, s0
	s_nop 0
	v_addc_co_u32_e32 v5, vcc, 0, v3, vcc
	global_store_short v[4:5], v6, off offset:1536
	v_lshl_add_u64 v[2:3], v[2:3], 0, s[44:45]
	v_cvt_pk_bf16_f32 v4, v14, s0
	global_store_short v[2:3], v4, off
	v_add_co_u32_e32 v4, vcc, 0x4000, v2
	v_cvt_pk_bf16_f32 v6, v15, s0
	s_nop 0
	v_addc_co_u32_e32 v5, vcc, 0, v3, vcc
	global_store_short v[4:5], v6, off offset:512
	v_add_co_u32_e32 v4, vcc, 0x8000, v2
	v_cvt_pk_bf16_f32 v6, v16, s0
	s_nop 0
	v_addc_co_u32_e32 v5, vcc, 0, v3, vcc
	global_store_short v[4:5], v6, off offset:1024
	v_add_co_u32_e32 v4, vcc, 0xc000, v2
	v_cvt_pk_bf16_f32 v6, v17, s0
	s_nop 0
	v_addc_co_u32_e32 v5, vcc, 0, v3, vcc
	v_lshl_add_u64 v[2:3], v[2:3], 0, s[44:45]
	global_store_short v[4:5], v6, off offset:1536

; #define STT(BASE, MUL) { bf16_t* q_ = (BASE) + (size_t)(4 * h) * TOK; _Pragma("unroll") for (int mi = 0; mi < 4; ++mi) _Pragma("unroll") for (int g = 0; g < 4; ++g) { \
;       _Pragma("unroll") for (int e = 0; e < 4; ++e) q_[(size_t)e * TOK] = f2bf(acc[mi][NI][4 * g + e] * (MUL)); q_ += (size_t)8 * TOK; asm volatile("" : "+v"(q_)); } }
; template <int NI> DI void inproj_epi_reg(const Params& p, int layer, int nt, int tok, int h, f32x16 (&acc)[4][2]) {
;     ...
;   } else if (nt < 20) {
;     bf16_t* VT = (bf16_t*)(p.ws + O_RVT) + (size_t)((nt - 16) * 128) * TOK + tok;
;     STT(VT, 1.f);
.LBB0_236:
	s_andn2_saveexec_b64 s[14:15], s[14:15]
	s_cbranch_execz .LBB0_238
	v_readlane_b32 s16, v253, 56
	v_readlane_b32 s17, v253, 57
	v_lshl_add_u32 v68, v237, 7, v232
	v_mov_b32_e32 v133, v181
	v_mov_b64_e32 v[66:67], s[16:17]
	s_ashr_i32 s7, s6, 31
	v_mad_u64_u32 v[66:67], s[16:17], v68, s29, v[66:67]
	v_lshl_add_u64 v[68:69], v[132:133], 0, s[6:7]
	v_lshl_add_u64 v[66:67], v[68:69], 1, v[66:67]
	v_mul_u32_u24_e32 v68, 0x8400, v193
	v_lshlrev_b32_e32 v180, 1, v68
	v_lshl_add_u64 v[66:67], v[66:67], 0, v[180:181]
	v_cvt_pk_bf16_f32 v50, v50, s0
	global_store_short v[66:67], v50, off offset:576
	v_add_co_u32_e32 v50, vcc, s48, v66
	v_cvt_pk_bf16_f32 v68, v51, s0
	s_nop 0
	v_addc_co_u32_e32 v51, vcc, 0, v67, vcc
	s_mov_b32 s16, 0x8000
	global_store_short v[50:51], v68, off offset:1088
	v_add_co_u32_e32 v50, vcc, s16, v66
	v_cvt_pk_bf16_f32 v52, v52, s0
	s_nop 0
	v_addc_co_u32_e32 v51, vcc, 0, v67, vcc
	s_mov_b32 s7, 0xc000
	global_store_short v[50:51], v52, off offset:1600
	v_add_co_u32_e32 v50, vcc, s7, v66
	v_cvt_pk_bf16_f32 v52, v53, s0
	s_nop 0
	v_addc_co_u32_e32 v51, vcc, 0, v67, vcc
	s_mov_b64 s[18:19], 0x21240
	global_store_short v[50:51], v52, off offset:2112
	v_lshl_add_u64 v[50:51], v[66:67], 0, s[18:19]
	v_cvt_pk_bf16_f32 v52, v54, s0
	global_store_short v[50:51], v52, off
	v_add_co_u32_e32 v52, vcc, s48, v50
	v_cvt_pk_bf16_f32 v54, v55, s0
	s_nop 0
	v_addc_co_u32_e32 v53, vcc, 0, v51, vcc
	global_store_short v[52:53], v54, off offset:512
	v_add_co_u32_e32 v52, vcc, s16, v50
	v_cvt_pk_bf16_f32 v54, v56, s0
	s_nop 0
	v_addc_co_u32_e32 v53, vcc, 0, v51, vcc
	global_store_short v[52:53], v54, off offset:1024
	v_add_co_u32_e32 v52, vcc, s7, v50
	v_cvt_pk_bf16_f32 v54, v57, s0
	s_nop 0
	v_addc_co_u32_e32 v53, vcc, 0, v51, vcc
	s_mov_b64 s[18:19], 0x21000
	global_store_short v[52:53], v54, off offset:1536
	v_lshl_add_u64 v[50:51], v[50:51], 0, s[18:19]
	v_cvt_pk_bf16_f32 v52, v58, s0
	global_store_short v[50:51], v52, off
	v_add_co_u32_e32 v52, vcc, s48, v50
	v_cvt_pk_bf16_f32 v54, v59, s0
	s_nop 0
	v_addc_co_u32_e32 v53, vcc, 0, v51, vcc
	global_store_short v[52:53], v54, off offset:512
	v_add_co_u32_e32 v52, vcc, s16, v50
	v_cvt_pk_bf16_f32 v54, v60, s0
	s_nop 0
	v_addc_co_u32_e32 v53, vcc, 0, v51, vcc
	global_store_short v[52:53], v54, off offset:1024
	v_add_co_u32_e32 v52, vcc, s7, v50
	v_cvt_pk_bf16_f32 v54, v61, s0
	s_nop 0
	v_addc_co_u32_e32 v53, vcc, 0, v51, vcc
	global_store_short v[52:53], v54, off offset:1536
	v_lshl_add_u64 v[50:51], v[50:51], 0, s[18:19]
	v_cvt_pk_bf16_f32 v52, v62, s0
	global_store_short v[50:51], v52, off
	v_add_co_u32_e32 v52, vcc, s48, v50
	v_cvt_pk_bf16_f32 v54, v63, s0
	s_nop 0
	v_addc_co_u32_e32 v53, vcc, 0, v51, vcc
	global_store_short v[52:53], v54, off offset:512
	v_add_co_u32_e32 v52, vcc, s16, v50
	v_cvt_pk_bf16_f32 v54, v64, s0
	s_nop 0
	v_addc_co_u32_e32 v53, vcc, 0, v51, vcc
	global_store_short v[52:53], v54, off offset:1024
	v_add_co_u32_e32 v52, vcc, s7, v50
	v_cvt_pk_bf16_f32 v54, v65, s0
	s_nop 0
	v_addc_co_u32_e32 v53, vcc, 0, v51, vcc
	v_lshl_add_u64 v[50:51], v[50:51], 0, s[18:19]
	v_cvt_pk_bf16_f32 v34, v34, s0
	global_store_short v[52:53], v54, off offset:1536
	global_store_short v[50:51], v34, off
	v_add_co_u32_e32 v34, vcc, s48, v50
	v_cvt_pk_bf16_f32 v52, v35, s0
	s_nop 0
	v_addc_co_u32_e32 v35, vcc, 0, v51, vcc
	global_store_short v[34:35], v52, off offset:512
	v_add_co_u32_e32 v34, vcc, s16, v50
	v_cvt_pk_bf16_f32 v36, v36, s0
	s_nop 0
	v_addc_co_u32_e32 v35, vcc, 0, v51, vcc
	global_store_short v[34:35], v36, off offset:1024
	v_add_co_u32_e32 v34, vcc, s7, v50
	v_cvt_pk_bf16_f32 v36, v37, s0
	s_nop 0
	v_addc_co_u32_e32 v35, vcc, 0, v51, vcc
	global_store_short v[34:35], v36, off offset:1536
	v_lshl_add_u64 v[34:35], v[50:51], 0, s[18:19]
	v_cvt_pk_bf16_f32 v36, v38, s0
	global_store_short v[34:35], v36, off
	v_add_co_u32_e32 v36, vcc, s48, v34
	v_cvt_pk_bf16_f32 v38, v39, s0
	s_nop 0
	v_addc_co_u32_e32 v37, vcc, 0, v35, vcc
	global_store_short v[36:37], v38, off offset:512
	v_add_co_u32_e32 v36, vcc, s16, v34
	v_cvt_pk_bf16_f32 v38, v40, s0
	s_nop 0
	v_addc_co_u32_e32 v37, vcc, 0, v35, vcc
	global_store_short v[36:37], v38, off offset:1024
	v_add_co_u32_e32 v36, vcc, s7, v34
	v_cvt_pk_bf16_f32 v38, v41, s0
	s_nop 0
	v_addc_co_u32_e32 v37, vcc, 0, v35, vcc
	global_store_short v[36:37], v38, off offset:1536
	v_lshl_add_u64 v[34:35], v[34:35], 0, s[18:19]
	v_cvt_pk_bf16_f32 v36, v42, s0
	global_store_short v[34:35], v36, off
	v_add_co_u32_e32 v36, vcc, s48, v34
	v_cvt_pk_bf16_f32 v38, v43, s0
	s_nop 0
	v_addc_co_u32_e32 v37, vcc, 0, v35, vcc
	global_store_short v[36:37], v38, off offset:512
	v_add_co_u32_e32 v36, vcc, s16, v34
	v_cvt_pk_bf16_f32 v38, v44, s0
	s_nop 0
	v_addc_co_u32_e32 v37, vcc, 0, v35, vcc
	global_store_short v[36:37], v38, off offset:1024
	v_add_co_u32_e32 v36, vcc, s7, v34
	v_cvt_pk_bf16_f32 v38, v45, s0
	s_nop 0
	v_addc_co_u32_e32 v37, vcc, 0, v35, vcc
	global_store_short v[36:37], v38, off offset:1536
	v_lshl_add_u64 v[34:35], v[34:35], 0, s[18:19]
	v_cvt_pk_bf16_f32 v36, v46, s0
	global_store_short v[34:35], v36, off
	v_add_co_u32_e32 v36, vcc, s48, v34
	v_cvt_pk_bf16_f32 v38, v47, s0
	s_nop 0
	v_addc_co_u32_e32 v37, vcc, 0, v35, vcc
	global_store_short v[36:37], v38, off offset:512
; #define STT(BASE, MUL) { bf16_t* q_ = (BASE) + (size_t)(4 * h) * TOK; _Pragma("unroll") for (int mi = 0; mi < 4; ++mi) _Pragma("unroll") for (int g = 0; g < 4; ++g) { \
;       _Pragma("unroll") for (int e = 0; e < 4; ++e) q_[(size_t)e * TOK] = f2bf(acc[mi][NI][4 * g + e] * (MUL)); q_ += (size_t)8 * TOK; asm volatile("" : "+v"(q_)); } }
; template <int NI> DI void inproj_epi_reg(const Params& p, int layer, int nt, int tok, int h, f32x16 (&acc)[4][2]) {
;     ...
;   } else if (nt < 20) {
;     bf16_t* VT = (bf16_t*)(p.ws + O_RVT) + (size_t)((nt - 16) * 128) * TOK + tok;
;     STT(VT, 1.f);
	v_add_co_u32_e32 v36, vcc, s16, v34
	v_cvt_pk_bf16_f32 v38, v48, s0
	s_nop 0
	v_addc_co_u32_e32 v37, vcc, 0, v35, vcc
	global_store_short v[36:37], v38, off offset:1024
	v_add_co_u32_e32 v36, vcc, s7, v34
	v_cvt_pk_bf16_f32 v38, v49, s0
	s_nop 0
	v_addc_co_u32_e32 v37, vcc, 0, v35, vcc
	v_lshl_add_u64 v[34:35], v[34:35], 0, s[18:19]
	v_cvt_pk_bf16_f32 v18, v18, s0
	global_store_short v[36:37], v38, off offset:1536
	global_store_short v[34:35], v18, off
	v_add_co_u32_e32 v18, vcc, s48, v34
	v_cvt_pk_bf16_f32 v36, v19, s0
	s_nop 0
	v_addc_co_u32_e32 v19, vcc, 0, v35, vcc
	global_store_short v[18:19], v36, off offset:512
	v_add_co_u32_e32 v18, vcc, s16, v34
	v_cvt_pk_bf16_f32 v20, v20, s0
	s_nop 0
	v_addc_co_u32_e32 v19, vcc, 0, v35, vcc
	global_store_short v[18:19], v20, off offset:1024
	v_add_co_u32_e32 v18, vcc, s7, v34
	v_cvt_pk_bf16_f32 v20, v21, s0
	s_nop 0
	v_addc_co_u32_e32 v19, vcc, 0, v35, vcc
	global_store_short v[18:19], v20, off offset:1536
	v_lshl_add_u64 v[18:19], v[34:35], 0, s[18:19]
	v_cvt_pk_bf16_f32 v20, v22, s0
	global_store_short v[18:19], v20, off
	v_add_co_u32_e32 v20, vcc, s48, v18
	v_cvt_pk_bf16_f32 v22, v23, s0
	s_nop 0
	v_addc_co_u32_e32 v21, vcc, 0, v19, vcc
	global_store_short v[20:21], v22, off offset:512
	v_add_co_u32_e32 v20, vcc, s16, v18
	v_cvt_pk_bf16_f32 v22, v24, s0
	s_nop 0
	v_addc_co_u32_e32 v21, vcc, 0, v19, vcc
	global_store_short v[20:21], v22, off offset:1024
	v_add_co_u32_e32 v20, vcc, s7, v18
	v_cvt_pk_bf16_f32 v22, v25, s0
	s_nop 0
	v_addc_co_u32_e32 v21, vcc, 0, v19, vcc
	global_store_short v[20:21], v22, off offset:1536
	v_lshl_add_u64 v[18:19], v[18:19], 0, s[18:19]
	v_cvt_pk_bf16_f32 v20, v26, s0
	global_store_short v[18:19], v20, off
	v_add_co_u32_e32 v20, vcc, s48, v18
	v_cvt_pk_bf16_f32 v22, v27, s0
	s_nop 0
	v_addc_co_u32_e32 v21, vcc, 0, v19, vcc
	global_store_short v[20:21], v22, off offset:512
	v_add_co_u32_e32 v20, vcc, s16, v18
	v_cvt_pk_bf16_f32 v22, v28, s0
	s_nop 0
	v_addc_co_u32_e32 v21, vcc, 0, v19, vcc
	global_store_short v[20:21], v22, off offset:1024
	v_add_co_u32_e32 v20, vcc, s7, v18
	v_cvt_pk_bf16_f32 v22, v29, s0
	s_nop 0
	v_addc_co_u32_e32 v21, vcc, 0, v19, vcc
	global_store_short v[20:21], v22, off offset:1536
	v_lshl_add_u64 v[18:19], v[18:19], 0, s[18:19]
	v_cvt_pk_bf16_f32 v20, v30, s0
	global_store_short v[18:19], v20, off
	v_add_co_u32_e32 v20, vcc, s48, v18
	v_cvt_pk_bf16_f32 v22, v31, s0
	s_nop 0
	v_addc_co_u32_e32 v21, vcc, 0, v19, vcc
	global_store_short v[20:21], v22, off offset:512
	v_add_co_u32_e32 v20, vcc, s16, v18
	v_cvt_pk_bf16_f32 v22, v32, s0
	s_nop 0
	v_addc_co_u32_e32 v21, vcc, 0, v19, vcc
	global_store_short v[20:21], v22, off offset:1024
	v_add_co_u32_e32 v20, vcc, s7, v18
	v_cvt_pk_bf16_f32 v22, v33, s0
	s_nop 0
	v_addc_co_u32_e32 v21, vcc, 0, v19, vcc
	v_lshl_add_u64 v[18:19], v[18:19], 0, s[18:19]
	v_cvt_pk_bf16_f32 v2, v2, s0
	global_store_short v[20:21], v22, off offset:1536
	global_store_short v[18:19], v2, off
	v_add_co_u32_e32 v2, vcc, s48, v18
	v_cvt_pk_bf16_f32 v20, v3, s0
	s_nop 0
	v_addc_co_u32_e32 v3, vcc, 0, v19, vcc
	global_store_short v[2:3], v20, off offset:512
	v_add_co_u32_e32 v2, vcc, s16, v18
	v_cvt_pk_bf16_f32 v4, v4, s0
	s_nop 0
	v_addc_co_u32_e32 v3, vcc, 0, v19, vcc
	global_store_short v[2:3], v4, off offset:1024
	v_add_co_u32_e32 v2, vcc, s7, v18
	v_cvt_pk_bf16_f32 v4, v5, s0
	s_nop 0
	v_addc_co_u32_e32 v3, vcc, 0, v19, vcc
	global_store_short v[2:3], v4, off offset:1536
	v_lshl_add_u64 v[2:3], v[18:19], 0, s[18:19]
	v_cvt_pk_bf16_f32 v4, v6, s0
	global_store_short v[2:3], v4, off
	v_add_co_u32_e32 v4, vcc, s48, v2
	v_cvt_pk_bf16_f32 v6, v7, s0
	s_nop 0
	v_addc_co_u32_e32 v5, vcc, 0, v3, vcc
	global_store_short v[4:5], v6, off offset:512
	v_add_co_u32_e32 v4, vcc, s16, v2
	v_cvt_pk_bf16_f32 v6, v8, s0
	s_nop 0
	v_addc_co_u32_e32 v5, vcc, 0, v3, vcc
	global_store_short v[4:5], v6, off offset:1024
	v_add_co_u32_e32 v4, vcc, s7, v2
	v_cvt_pk_bf16_f32 v6, v9, s0
	s_nop 0
	v_addc_co_u32_e32 v5, vcc, 0, v3, vcc
	global_store_short v[4:5], v6, off offset:1536
	v_lshl_add_u64 v[2:3], v[2:3], 0, s[18:19]
	v_cvt_pk_bf16_f32 v4, v10, s0
	global_store_short v[2:3], v4, off
	v_add_co_u32_e32 v4, vcc, s48, v2
	v_cvt_pk_bf16_f32 v6, v11, s0
	s_nop 0
	v_addc_co_u32_e32 v5, vcc, 0, v3, vcc
	global_store_short v[4:5], v6, off offset:512
	v_add_co_u32_e32 v4, vcc, 0x8000, v2
	v_cvt_pk_bf16_f32 v6, v12, s0
	s_nop 0
	v_addc_co_u32_e32 v5, vcc, 0, v3, vcc
	global_store_short v[4:5], v6, off offset:1024
	v_add_co_u32_e32 v4, vcc, s7, v2
	v_cvt_pk_bf16_f32 v6, v13, s0
	s_nop 0
	v_addc_co_u32_e32 v5, vcc, 0, v3, vcc
	global_store_short v[4:5], v6, off offset:1536
	v_lshl_add_u64 v[2:3], v[2:3], 0, s[18:19]
	v_cvt_pk_bf16_f32 v4, v14, s0
	global_store_short v[2:3], v4, off
	v_add_co_u32_e32 v4, vcc, 0x4000, v2
	v_cvt_pk_bf16_f32 v6, v15, s0
	s_nop 0
	v_addc_co_u32_e32 v5, vcc, 0, v3, vcc
	global_store_short v[4:5], v6, off offset:512
	v_add_co_u32_e32 v4, vcc, 0x8000, v2
	v_cvt_pk_bf16_f32 v6, v16, s0
	s_nop 0
	v_addc_co_u32_e32 v5, vcc, 0, v3, vcc
	global_store_short v[4:5], v6, off offset:1024
	v_add_co_u32_e32 v4, vcc, 0xc000, v2
	v_cvt_pk_bf16_f32 v6, v17, s0
	s_nop 0
	v_addc_co_u32_e32 v5, vcc, 0, v3, vcc
	v_lshl_add_u64 v[2:3], v[2:3], 0, s[18:19]
	global_store_short v[4:5], v6, off offset:1536

; DI float ex2(float x) { return __builtin_amdgcn_exp2f(x); }
; #define ST4(BASE) { _Pragma("unroll") for (int mi = 0; mi < 4; ++mi) _Pragma("unroll") for (int g = 0; g < 4; ++g) { \
;       u32x2 o_; o_.x = pack2(acc[mi][NI][4 * g], acc[mi][NI][4 * g + 1]); o_.y = pack2(acc[mi][NI][4 * g + 2], acc[mi][NI][4 * g + 3]); *(u32x2*)((BASE) + 32 * mi + 8 * g + 4 * h) = o_; } }
; #define STT(BASE, MUL) { bf16_t* q_ = (BASE) + (size_t)(4 * h) * TOK; _Pragma("unroll") for (int mi = 0; mi < 4; ++mi) _Pragma("unroll") for (int g = 0; g < 4; ++g) { \
;       _Pragma("unroll") for (int e = 0; e < 4; ++e) q_[(size_t)e * TOK] = f2bf(acc[mi][NI][4 * g + e] * (MUL)); q_ += (size_t)8 * TOK; asm volatile("" : "+v"(q_)); } }
; template <int NI> DI void inproj_epi_reg(const Params& p, int layer, int nt, int tok, int h, f32x16 (&acc)[4][2]) {
;     ...
;       const float scale = 0.08838834764831845f;
;       const float lgf = scal[layer * 8 + hd], lgb = scal[layer * 8 + 4 + hd];
;       const int j = tok & 127;
;       const float df = ex2((float)(127 - j) * lgf * LOG2E), db = ex2((float)j * lgb * LOG2E);
; #pragma unroll
;       for (int mi = 0; mi < 4; ++mi)
; #pragma unroll
;         for (int reg = 0; reg < 16; ++reg) acc[mi][NI][reg] *= scale;
;       bf16_t* RK = (bf16_t*)(p.ws + O_RK) + (size_t)tok * 512 + hd * 128;
;       ST4(RK);
;       bf16_t* KF = (bf16_t*)(p.ws + O_RKTF) + (size_t)(hd * 128) * TOK + tok;
;       bf16_t* KB = (bf16_t*)(p.ws + O_RKTB) + (size_t)(hd * 128) * TOK + tok;
;       STT(KF, df);
.LBB0_242:
	s_andn2_saveexec_b64 s[14:15], s[14:15]
	s_cbranch_execz .LBB0_244
	v_readlane_b32 s7, v255, 0
	v_readlane_b32 s16, v252, 36
	v_mov_b32_e32 v17, v181
	v_or_b32_e32 v16, s7, v89
	v_readlane_b32 s17, v252, 37
	s_movk_i32 s7, 0x7f
	v_bitop3_b32 v27, v66, s7, v66 bitop3:0xc
	v_lshl_add_u64 v[16:17], v[16:17], 2, s[16:17]
	global_load_dword v26, v[16:17], off
	s_nop 0
	global_load_dword v16, v[16:17], off offset:16
	v_and_b32_e32 v17, 0x7f, v66
	v_cvt_f32_ubyte0_e32 v27, v27
	v_cvt_f32_ubyte0_e32 v17, v17
	s_mov_b32 s16, 0x3db504f3
	v_pk_mul_f32 v[80:81], v[68:69], s[16:17] op_sel_hi:[1,0]
	v_pk_mul_f32 v[76:77], v[50:51], s[16:17] op_sel_hi:[1,0]
	v_pk_mul_f32 v[74:75], v[52:53], s[16:17] op_sel_hi:[1,0]
	v_pk_mul_f32 v[72:73], v[54:55], s[16:17] op_sel_hi:[1,0]
	v_pk_mul_f32 v[70:71], v[56:57], s[16:17] op_sel_hi:[1,0]
	v_pk_mul_f32 v[68:69], v[58:59], s[16:17] op_sel_hi:[1,0]
	v_pk_mul_f32 v[60:61], v[60:61], s[16:17] op_sel_hi:[1,0]
	v_pk_mul_f32 v[58:59], v[62:63], s[16:17] op_sel_hi:[1,0]
	v_pk_mul_f32 v[56:57], v[34:35], s[16:17] op_sel_hi:[1,0]
	v_pk_mul_f32 v[54:55], v[36:37], s[16:17] op_sel_hi:[1,0]
	v_pk_mul_f32 v[52:53], v[38:39], s[16:17] op_sel_hi:[1,0]
	v_pk_mul_f32 v[50:51], v[40:41], s[16:17] op_sel_hi:[1,0]
	v_pk_mul_f32 v[40:41], v[42:43], s[16:17] op_sel_hi:[1,0]
	v_pk_mul_f32 v[38:39], v[44:45], s[16:17] op_sel_hi:[1,0]
	v_pk_mul_f32 v[36:37], v[46:47], s[16:17] op_sel_hi:[1,0]
	v_pk_mul_f32 v[34:35], v[48:49], s[16:17] op_sel_hi:[1,0]
	v_pk_mul_f32 v[32:33], v[64:65], s[16:17] op_sel_hi:[1,0]
	v_pk_mul_f32 v[30:31], v[18:19], s[16:17] op_sel_hi:[1,0]
	v_pk_mul_f32 v[28:29], v[20:21], s[16:17] op_sel_hi:[1,0]
	v_pk_mul_f32 v[24:25], v[24:25], s[16:17] op_sel_hi:[1,0]
	v_pk_mul_f32 v[20:21], v[12:13], s[16:17] op_sel_hi:[1,0]
	v_pk_mul_f32 v[18:19], v[14:15], s[16:17] op_sel_hi:[1,0]
	v_pk_mul_f32 v[14:15], v[4:5], s[16:17] op_sel_hi:[1,0]
	v_pk_mul_f32 v[12:13], v[6:7], s[16:17] op_sel_hi:[1,0]
	v_pk_mul_f32 v[6:7], v[82:83], s[16:17] op_sel_hi:[1,0]
	v_pk_mul_f32 v[4:5], v[84:85], s[16:17] op_sel_hi:[1,0]
	v_lshlrev_b32_e32 v47, 7, v89
	v_mov_b32_e32 v89, v181
	v_cvt_pk_bf16_f32 v44, v80, v81
	v_cvt_pk_bf16_f32 v45, v76, v77
	v_mov_b32_e32 v133, v181
	s_ashr_i32 s7, s6, 31
	s_mov_b64 s[18:19], 0x21000
	s_waitcnt vmcnt(0)
	v_mul_f32_e32 v26, v26, v27
	v_mul_f32_e32 v67, 0x3fb8aa3b, v26
	v_mul_f32_e32 v16, v16, v17
	v_mul_f32_e32 v90, 0x3fb8aa3b, v16
	v_pk_mul_f32 v[26:27], v[22:23], s[16:17] op_sel_hi:[1,0]
	v_pk_mul_f32 v[22:23], v[10:11], s[16:17] op_sel_hi:[1,0]
	v_pk_mul_f32 v[16:17], v[2:3], s[16:17] op_sel_hi:[1,0]
	v_pk_mul_f32 v[10:11], v[8:9], s[16:17] op_sel_hi:[1,0]
	v_pk_mul_f32 v[8:9], v[78:79], s[16:17] op_sel_hi:[1,0]
	v_pk_mul_f32 v[2:3], v[86:87], s[16:17] op_sel_hi:[1,0]
	v_exp_f32_e32 v46, v67
	v_ashrrev_i32_e32 v67, 31, v66
	v_readlane_b32 s16, v253, 60
	v_lshlrev_b64 v[42:43], 10, v[66:67]
	v_readlane_b32 s17, v253, 61
	s_nop 1
	v_lshl_add_u64 v[42:43], s[16:17], 0, v[42:43]
	v_lshl_add_u64 v[42:43], v[42:43], 0, v[180:181]
	v_lshl_add_u64 v[42:43], v[42:43], 0, v[88:89]
	global_store_dwordx2 v[42:43], v[44:45], off
	v_cvt_pk_bf16_f32 v44, v74, v75
	v_cvt_pk_bf16_f32 v45, v72, v73
	global_store_dwordx2 v[42:43], v[44:45], off offset:16
	v_cvt_pk_bf16_f32 v44, v70, v71
	v_cvt_pk_bf16_f32 v45, v68, v69
	global_store_dwordx2 v[42:43], v[44:45], off offset:32
	v_cvt_pk_bf16_f32 v44, v60, v61
	v_cvt_pk_bf16_f32 v45, v58, v59
	global_store_dwordx2 v[42:43], v[44:45], off offset:48
	v_cvt_pk_bf16_f32 v44, v56, v57
	v_cvt_pk_bf16_f32 v45, v54, v55
	global_store_dwordx2 v[42:43], v[44:45], off offset:64
	v_cvt_pk_bf16_f32 v44, v52, v53
	v_cvt_pk_bf16_f32 v45, v50, v51
	global_store_dwordx2 v[42:43], v[44:45], off offset:80
	v_cvt_pk_bf16_f32 v44, v40, v41
	v_cvt_pk_bf16_f32 v45, v38, v39
	global_store_dwordx2 v[42:43], v[44:45], off offset:96
	v_cvt_pk_bf16_f32 v44, v36, v37
	v_cvt_pk_bf16_f32 v45, v34, v35
	global_store_dwordx2 v[42:43], v[44:45], off offset:112
	v_cvt_pk_bf16_f32 v44, v32, v33
	v_cvt_pk_bf16_f32 v45, v30, v31
	global_store_dwordx2 v[42:43], v[44:45], off offset:128
	v_cvt_pk_bf16_f32 v44, v28, v29
	v_cvt_pk_bf16_f32 v45, v26, v27
	global_store_dwordx2 v[42:43], v[44:45], off offset:144
	v_cvt_pk_bf16_f32 v44, v24, v25
	v_cvt_pk_bf16_f32 v45, v22, v23
	global_store_dwordx2 v[42:43], v[44:45], off offset:160
	v_cvt_pk_bf16_f32 v44, v20, v21
	v_cvt_pk_bf16_f32 v45, v18, v19
	global_store_dwordx2 v[42:43], v[44:45], off offset:176
	v_cvt_pk_bf16_f32 v44, v16, v17
	v_cvt_pk_bf16_f32 v45, v14, v15
	global_store_dwordx2 v[42:43], v[44:45], off offset:192
	v_cvt_pk_bf16_f32 v44, v12, v13
	v_cvt_pk_bf16_f32 v45, v10, v11
	global_store_dwordx2 v[42:43], v[44:45], off offset:208
	v_cvt_pk_bf16_f32 v44, v8, v9
	v_cvt_pk_bf16_f32 v45, v6, v7
	global_store_dwordx2 v[42:43], v[44:45], off offset:224
	v_cvt_pk_bf16_f32 v44, v4, v5
	v_cvt_pk_bf16_f32 v45, v2, v3
	global_store_dwordx2 v[42:43], v[44:45], off offset:240
	v_mul_u32_u24_e32 v42, 0x2100, v47
	v_readlane_b32 s16, v253, 62
	v_lshlrev_b32_e32 v180, 1, v42
	v_readlane_b32 s17, v253, 63
	v_lshl_add_u64 v[42:43], v[132:133], 0, s[6:7]
	v_readlane_b32 s6, v254, 0
	v_lshl_add_u64 v[44:45], s[16:17], 0, v[180:181]
	v_lshl_add_u64 v[42:43], v[42:43], 1, 64
	v_readlane_b32 s7, v254, 1
	v_mul_u32_u24_e32 v47, 0x8400, v193
	v_lshl_add_u64 v[48:49], v[44:45], 0, v[42:43]
	v_lshl_add_u64 v[44:45], s[6:7], 0, v[180:181]
	v_lshlrev_b32_e32 v180, 1, v47
	v_mul_f32_e32 v47, v80, v46
	v_lshl_add_u64 v[48:49], v[48:49], 0, v[180:181]
	v_cvt_pk_bf16_f32 v47, v47, s0
	global_store_short v[48:49], v47, off offset:512
	v_mul_f32_e32 v47, v81, v46
; #define STT(BASE, MUL) { bf16_t* q_ = (BASE) + (size_t)(4 * h) * TOK; _Pragma("unroll") for (int mi = 0; mi < 4; ++mi) _Pragma("unroll") for (int g = 0; g < 4; ++g) { \
;       _Pragma("unroll") for (int e = 0; e < 4; ++e) q_[(size_t)e * TOK] = f2bf(acc[mi][NI][4 * g + e] * (MUL)); q_ += (size_t)8 * TOK; asm volatile("" : "+v"(q_)); } }
; template <int NI> DI void inproj_epi_reg(const Params& p, int layer, int nt, int tok, int h, f32x16 (&acc)[4][2]) {
;     ...
;       bf16_t* KF = (bf16_t*)(p.ws + O_RKTF) + (size_t)(hd * 128) * TOK + tok;
;       bf16_t* KB = (bf16_t*)(p.ws + O_RKTB) + (size_t)(hd * 128) * TOK + tok;
;       STT(KF, df);
	v_add_co_u32_e32 v62, vcc, s48, v48
	v_cvt_pk_bf16_f32 v47, v47, s0
	s_nop 0
	v_addc_co_u32_e32 v63, vcc, 0, v49, vcc
	s_mov_b32 s7, 0x8000
	global_store_short v[62:63], v47, off offset:1024
	v_mul_f32_e32 v47, v76, v46
	v_add_co_u32_e32 v62, vcc, s7, v48
	v_cvt_pk_bf16_f32 v47, v47, s0
	s_nop 0
	v_addc_co_u32_e32 v63, vcc, 0, v49, vcc
	s_mov_b32 s6, 0xc000
	global_store_short v[62:63], v47, off offset:1536
	v_mul_f32_e32 v47, v77, v46
	v_add_co_u32_e32 v62, vcc, s6, v48
	v_cvt_pk_bf16_f32 v47, v47, s0
	s_nop 0
	v_addc_co_u32_e32 v63, vcc, 0, v49, vcc
	global_store_short v[62:63], v47, off offset:2048
	s_mov_b64 s[16:17], 0x21200
	v_mul_f32_e32 v47, v74, v46
	v_lshl_add_u64 v[48:49], v[48:49], 0, s[16:17]
	v_cvt_pk_bf16_f32 v47, v47, s0
	global_store_short v[48:49], v47, off
	v_mul_f32_e32 v47, v75, v46
	v_add_co_u32_e32 v62, vcc, s48, v48
	v_cvt_pk_bf16_f32 v47, v47, s0
	s_nop 0
	v_addc_co_u32_e32 v63, vcc, 0, v49, vcc
	global_store_short v[62:63], v47, off offset:512
	v_mul_f32_e32 v47, v72, v46
	v_add_co_u32_e32 v62, vcc, s7, v48
	v_cvt_pk_bf16_f32 v47, v47, s0
	s_nop 0
	v_addc_co_u32_e32 v63, vcc, 0, v49, vcc
	global_store_short v[62:63], v47, off offset:1024
	v_mul_f32_e32 v47, v73, v46
	v_add_co_u32_e32 v62, vcc, s6, v48
	v_cvt_pk_bf16_f32 v47, v47, s0
	s_nop 0
	v_addc_co_u32_e32 v63, vcc, 0, v49, vcc
	global_store_short v[62:63], v47, off offset:1536
	v_mul_f32_e32 v47, v70, v46
	v_lshl_add_u64 v[48:49], v[48:49], 0, s[18:19]
	v_cvt_pk_bf16_f32 v47, v47, s0
	global_store_short v[48:49], v47, off
	v_mul_f32_e32 v47, v71, v46
	v_add_co_u32_e32 v62, vcc, s48, v48
	v_cvt_pk_bf16_f32 v47, v47, s0
	s_nop 0
	v_addc_co_u32_e32 v63, vcc, 0, v49, vcc
	global_store_short v[62:63], v47, off offset:512
	v_mul_f32_e32 v47, v68, v46
	v_add_co_u32_e32 v62, vcc, s7, v48
	v_cvt_pk_bf16_f32 v47, v47, s0
	s_nop 0
	v_addc_co_u32_e32 v63, vcc, 0, v49, vcc
	global_store_short v[62:63], v47, off offset:1024
	v_mul_f32_e32 v47, v69, v46
	v_add_co_u32_e32 v62, vcc, s6, v48
	v_cvt_pk_bf16_f32 v47, v47, s0
	s_nop 0
	v_addc_co_u32_e32 v63, vcc, 0, v49, vcc
	global_store_short v[62:63], v47, off offset:1536
	v_mul_f32_e32 v47, v60, v46
	v_lshl_add_u64 v[48:49], v[48:49], 0, s[18:19]
	v_cvt_pk_bf16_f32 v47, v47, s0
	global_store_short v[48:49], v47, off
	v_mul_f32_e32 v47, v61, v46
	v_add_co_u32_e32 v62, vcc, s48, v48
	v_cvt_pk_bf16_f32 v47, v47, s0
	s_nop 0
	v_addc_co_u32_e32 v63, vcc, 0, v49, vcc
	global_store_short v[62:63], v47, off offset:512
	v_mul_f32_e32 v47, v58, v46
	v_add_co_u32_e32 v62, vcc, s7, v48
	v_cvt_pk_bf16_f32 v47, v47, s0
	s_nop 0
	v_addc_co_u32_e32 v63, vcc, 0, v49, vcc
	global_store_short v[62:63], v47, off offset:1024
	v_mul_f32_e32 v47, v59, v46
	v_add_co_u32_e32 v62, vcc, s6, v48
	v_cvt_pk_bf16_f32 v47, v47, s0
	s_nop 0
	v_addc_co_u32_e32 v63, vcc, 0, v49, vcc
	global_store_short v[62:63], v47, off offset:1536
	v_mul_f32_e32 v47, v56, v46
	v_lshl_add_u64 v[48:49], v[48:49], 0, s[18:19]
	v_cvt_pk_bf16_f32 v47, v47, s0
	global_store_short v[48:49], v47, off
	v_mul_f32_e32 v47, v57, v46
	v_add_co_u32_e32 v62, vcc, s48, v48
	v_cvt_pk_bf16_f32 v47, v47, s0
	s_nop 0
	v_addc_co_u32_e32 v63, vcc, 0, v49, vcc
	global_store_short v[62:63], v47, off offset:512
	v_mul_f32_e32 v47, v54, v46
	v_add_co_u32_e32 v62, vcc, s7, v48
	v_cvt_pk_bf16_f32 v47, v47, s0
	s_nop 0
	v_addc_co_u32_e32 v63, vcc, 0, v49, vcc
	global_store_short v[62:63], v47, off offset:1024
	v_mul_f32_e32 v47, v55, v46
	v_add_co_u32_e32 v62, vcc, s6, v48
	v_cvt_pk_bf16_f32 v47, v47, s0
	s_nop 0
	v_addc_co_u32_e32 v63, vcc, 0, v49, vcc
	global_store_short v[62:63], v47, off offset:1536
	v_mul_f32_e32 v47, v52, v46
	v_lshl_add_u64 v[48:49], v[48:49], 0, s[18:19]
	v_cvt_pk_bf16_f32 v47, v47, s0
	global_store_short v[48:49], v47, off
	v_mul_f32_e32 v47, v53, v46
	v_add_co_u32_e32 v62, vcc, s48, v48
	v_cvt_pk_bf16_f32 v47, v47, s0
	s_nop 0
	v_addc_co_u32_e32 v63, vcc, 0, v49, vcc
	global_store_short v[62:63], v47, off offset:512
	v_mul_f32_e32 v47, v50, v46
	v_add_co_u32_e32 v62, vcc, s7, v48
	v_cvt_pk_bf16_f32 v47, v47, s0
	s_nop 0
	v_addc_co_u32_e32 v63, vcc, 0, v49, vcc
	global_store_short v[62:63], v47, off offset:1024
	v_mul_f32_e32 v47, v51, v46
	v_add_co_u32_e32 v62, vcc, s6, v48
	v_cvt_pk_bf16_f32 v47, v47, s0
	s_nop 0
	v_addc_co_u32_e32 v63, vcc, 0, v49, vcc
	global_store_short v[62:63], v47, off offset:1536
	v_mul_f32_e32 v47, v40, v46
	v_lshl_add_u64 v[48:49], v[48:49], 0, s[18:19]
	v_cvt_pk_bf16_f32 v47, v47, s0
	global_store_short v[48:49], v47, off
	v_mul_f32_e32 v47, v41, v46
	v_add_co_u32_e32 v62, vcc, s48, v48
	v_cvt_pk_bf16_f32 v47, v47, s0
	s_nop 0
	v_addc_co_u32_e32 v63, vcc, 0, v49, vcc
	global_store_short v[62:63], v47, off offset:512
	v_mul_f32_e32 v47, v38, v46
	v_add_co_u32_e32 v62, vcc, s7, v48
	v_cvt_pk_bf16_f32 v47, v47, s0
	s_nop 0
	v_addc_co_u32_e32 v63, vcc, 0, v49, vcc
	global_store_short v[62:63], v47, off offset:1024
	v_mul_f32_e32 v47, v39, v46
	v_add_co_u32_e32 v62, vcc, s6, v48
	v_cvt_pk_bf16_f32 v47, v47, s0
	s_nop 0
	v_addc_co_u32_e32 v63, vcc, 0, v49, vcc
	global_store_short v[62:63], v47, off offset:1536
	v_mul_f32_e32 v47, v36, v46
	v_lshl_add_u64 v[48:49], v[48:49], 0, s[18:19]
	v_cvt_pk_bf16_f32 v47, v47, s0
	global_store_short v[48:49], v47, off
	v_mul_f32_e32 v47, v37, v46
	v_add_co_u32_e32 v62, vcc, s48, v48
	v_cvt_pk_bf16_f32 v47, v47, s0
	s_nop 0
	v_addc_co_u32_e32 v63, vcc, 0, v49, vcc
	global_store_short v[62:63], v47, off offset:512
	v_mul_f32_e32 v47, v34, v46
	v_add_co_u32_e32 v62, vcc, s7, v48
	v_cvt_pk_bf16_f32 v47, v47, s0
	s_nop 0
	v_addc_co_u32_e32 v63, vcc, 0, v49, vcc
	global_store_short v[62:63], v47, off offset:1024
; #define STT(BASE, MUL) { bf16_t* q_ = (BASE) + (size_t)(4 * h) * TOK; _Pragma("unroll") for (int mi = 0; mi < 4; ++mi) _Pragma("unroll") for (int g = 0; g < 4; ++g) { \
;       _Pragma("unroll") for (int e = 0; e < 4; ++e) q_[(size_t)e * TOK] = f2bf(acc[mi][NI][4 * g + e] * (MUL)); q_ += (size_t)8 * TOK; asm volatile("" : "+v"(q_)); } }
; template <int NI> DI void inproj_epi_reg(const Params& p, int layer, int nt, int tok, int h, f32x16 (&acc)[4][2]) {
;     ...
;       bf16_t* KF = (bf16_t*)(p.ws + O_RKTF) + (size_t)(hd * 128) * TOK + tok;
;       bf16_t* KB = (bf16_t*)(p.ws + O_RKTB) + (size_t)(hd * 128) * TOK + tok;
;       STT(KF, df);
	v_mul_f32_e32 v47, v35, v46
	v_add_co_u32_e32 v62, vcc, s6, v48
	v_cvt_pk_bf16_f32 v47, v47, s0
	s_nop 0
	v_addc_co_u32_e32 v63, vcc, 0, v49, vcc
	global_store_short v[62:63], v47, off offset:1536
	v_mul_f32_e32 v47, v32, v46
	v_lshl_add_u64 v[48:49], v[48:49], 0, s[18:19]
	v_cvt_pk_bf16_f32 v47, v47, s0
	global_store_short v[48:49], v47, off
	v_mul_f32_e32 v47, v33, v46
	v_add_co_u32_e32 v62, vcc, s48, v48
	v_cvt_pk_bf16_f32 v47, v47, s0
	s_nop 0
	v_addc_co_u32_e32 v63, vcc, 0, v49, vcc
	global_store_short v[62:63], v47, off offset:512
	v_mul_f32_e32 v47, v30, v46
	v_add_co_u32_e32 v62, vcc, s7, v48
	v_cvt_pk_bf16_f32 v47, v47, s0
	s_nop 0
	v_addc_co_u32_e32 v63, vcc, 0, v49, vcc
	global_store_short v[62:63], v47, off offset:1024
	v_mul_f32_e32 v47, v31, v46
	v_add_co_u32_e32 v62, vcc, s6, v48
	v_cvt_pk_bf16_f32 v47, v47, s0
	s_nop 0
	v_addc_co_u32_e32 v63, vcc, 0, v49, vcc
	global_store_short v[62:63], v47, off offset:1536
	v_mul_f32_e32 v47, v28, v46
	v_lshl_add_u64 v[48:49], v[48:49], 0, s[18:19]
	v_cvt_pk_bf16_f32 v47, v47, s0
	global_store_short v[48:49], v47, off
	v_mul_f32_e32 v47, v29, v46
	v_add_co_u32_e32 v62, vcc, s48, v48
	v_cvt_pk_bf16_f32 v47, v47, s0
	s_nop 0
	v_addc_co_u32_e32 v63, vcc, 0, v49, vcc
	global_store_short v[62:63], v47, off offset:512
	v_mul_f32_e32 v47, v26, v46
	v_add_co_u32_e32 v62, vcc, s7, v48
	v_cvt_pk_bf16_f32 v47, v47, s0
	s_nop 0
	v_addc_co_u32_e32 v63, vcc, 0, v49, vcc
	global_store_short v[62:63], v47, off offset:1024
	v_mul_f32_e32 v47, v27, v46
	v_add_co_u32_e32 v62, vcc, s6, v48
	v_cvt_pk_bf16_f32 v47, v47, s0
	s_nop 0
	v_addc_co_u32_e32 v63, vcc, 0, v49, vcc
	global_store_short v[62:63], v47, off offset:1536
	v_mul_f32_e32 v47, v24, v46
	v_lshl_add_u64 v[48:49], v[48:49], 0, s[18:19]
	v_cvt_pk_bf16_f32 v47, v47, s0
	global_store_short v[48:49], v47, off
	v_mul_f32_e32 v47, v25, v46
	v_add_co_u32_e32 v62, vcc, s48, v48
	v_cvt_pk_bf16_f32 v47, v47, s0
	s_nop 0
	v_addc_co_u32_e32 v63, vcc, 0, v49, vcc
	global_store_short v[62:63], v47, off offset:512
	v_mul_f32_e32 v47, v22, v46
	v_add_co_u32_e32 v62, vcc, s7, v48
	v_cvt_pk_bf16_f32 v47, v47, s0
	s_nop 0
	v_addc_co_u32_e32 v63, vcc, 0, v49, vcc
	global_store_short v[62:63], v47, off offset:1024
	v_mul_f32_e32 v47, v23, v46
	v_add_co_u32_e32 v62, vcc, s6, v48
	v_cvt_pk_bf16_f32 v47, v47, s0
	s_nop 0
	v_addc_co_u32_e32 v63, vcc, 0, v49, vcc
	global_store_short v[62:63], v47, off offset:1536
	v_mul_f32_e32 v47, v20, v46
	v_lshl_add_u64 v[48:49], v[48:49], 0, s[18:19]
	v_cvt_pk_bf16_f32 v47, v47, s0
	global_store_short v[48:49], v47, off
	v_mul_f32_e32 v47, v21, v46
	v_add_co_u32_e32 v62, vcc, s48, v48
	v_cvt_pk_bf16_f32 v47, v47, s0
	s_nop 0
	v_addc_co_u32_e32 v63, vcc, 0, v49, vcc
	global_store_short v[62:63], v47, off offset:512
	v_mul_f32_e32 v47, v18, v46
	v_add_co_u32_e32 v62, vcc, s7, v48
	v_cvt_pk_bf16_f32 v47, v47, s0
	s_nop 0
	v_addc_co_u32_e32 v63, vcc, 0, v49, vcc
	global_store_short v[62:63], v47, off offset:1024
	v_mul_f32_e32 v47, v19, v46
	v_add_co_u32_e32 v62, vcc, s6, v48
	v_cvt_pk_bf16_f32 v47, v47, s0
	s_nop 0
	v_addc_co_u32_e32 v63, vcc, 0, v49, vcc
	global_store_short v[62:63], v47, off offset:1536
	v_mul_f32_e32 v47, v16, v46
	v_lshl_add_u64 v[48:49], v[48:49], 0, s[18:19]
	v_cvt_pk_bf16_f32 v47, v47, s0
	global_store_short v[48:49], v47, off
	v_mul_f32_e32 v47, v17, v46
	v_add_co_u32_e32 v62, vcc, s48, v48
	v_cvt_pk_bf16_f32 v47, v47, s0
	s_nop 0
	v_addc_co_u32_e32 v63, vcc, 0, v49, vcc
	global_store_short v[62:63], v47, off offset:512
	v_mul_f32_e32 v47, v14, v46
	v_add_co_u32_e32 v62, vcc, s7, v48
	v_cvt_pk_bf16_f32 v47, v47, s0
	s_nop 0
	v_addc_co_u32_e32 v63, vcc, 0, v49, vcc
	global_store_short v[62:63], v47, off offset:1024
	v_mul_f32_e32 v47, v15, v46
	v_add_co_u32_e32 v62, vcc, s6, v48
	v_cvt_pk_bf16_f32 v47, v47, s0
	s_nop 0
	v_addc_co_u32_e32 v63, vcc, 0, v49, vcc
	global_store_short v[62:63], v47, off offset:1536
	v_mul_f32_e32 v47, v12, v46
	v_lshl_add_u64 v[48:49], v[48:49], 0, s[18:19]
	v_cvt_pk_bf16_f32 v47, v47, s0
	global_store_short v[48:49], v47, off
	v_mul_f32_e32 v47, v13, v46
	v_add_co_u32_e32 v62, vcc, s48, v48
	v_cvt_pk_bf16_f32 v47, v47, s0
	s_nop 0
	v_addc_co_u32_e32 v63, vcc, 0, v49, vcc
	global_store_short v[62:63], v47, off offset:512
	v_mul_f32_e32 v47, v10, v46
	v_add_co_u32_e32 v62, vcc, s7, v48
	v_cvt_pk_bf16_f32 v47, v47, s0
	s_nop 0
	v_addc_co_u32_e32 v63, vcc, 0, v49, vcc
	global_store_short v[62:63], v47, off offset:1024
	v_mul_f32_e32 v47, v11, v46
	v_add_co_u32_e32 v62, vcc, s6, v48
	v_cvt_pk_bf16_f32 v47, v47, s0
	s_nop 0
	v_addc_co_u32_e32 v63, vcc, 0, v49, vcc
	global_store_short v[62:63], v47, off offset:1536
	v_mul_f32_e32 v47, v8, v46
	v_lshl_add_u64 v[48:49], v[48:49], 0, s[18:19]
	v_cvt_pk_bf16_f32 v47, v47, s0
	global_store_short v[48:49], v47, off
	v_mul_f32_e32 v47, v9, v46
	v_add_co_u32_e32 v62, vcc, s48, v48
	v_cvt_pk_bf16_f32 v47, v47, s0
	s_nop 0
	v_addc_co_u32_e32 v63, vcc, 0, v49, vcc
	global_store_short v[62:63], v47, off offset:512
	v_mul_f32_e32 v47, v6, v46
	v_add_co_u32_e32 v62, vcc, s7, v48
	v_cvt_pk_bf16_f32 v47, v47, s0
	s_nop 0
	v_addc_co_u32_e32 v63, vcc, 0, v49, vcc
	global_store_short v[62:63], v47, off offset:1024
	v_mul_f32_e32 v47, v7, v46
	v_add_co_u32_e32 v62, vcc, s6, v48
	v_cvt_pk_bf16_f32 v47, v47, s0
	s_nop 0
	v_addc_co_u32_e32 v63, vcc, 0, v49, vcc
	global_store_short v[62:63], v47, off offset:1536
	v_mul_f32_e32 v47, v4, v46
	v_lshl_add_u64 v[48:49], v[48:49], 0, s[18:19]
	v_cvt_pk_bf16_f32 v47, v47, s0
	global_store_short v[48:49], v47, off
	v_mul_f32_e32 v47, v5, v46
	v_add_co_u32_e32 v62, vcc, s48, v48
	v_cvt_pk_bf16_f32 v47, v47, s0
	s_nop 0
; #define STT(BASE, MUL) { bf16_t* q_ = (BASE) + (size_t)(4 * h) * TOK; _Pragma("unroll") for (int mi = 0; mi < 4; ++mi) _Pragma("unroll") for (int g = 0; g < 4; ++g) { \
;       _Pragma("unroll") for (int e = 0; e < 4; ++e) q_[(size_t)e * TOK] = f2bf(acc[mi][NI][4 * g + e] * (MUL)); q_ += (size_t)8 * TOK; asm volatile("" : "+v"(q_)); } }
; template <int NI> DI void inproj_epi_reg(const Params& p, int layer, int nt, int tok, int h, f32x16 (&acc)[4][2]) {
;     ...
;       STT(KF, df);
;       STT(KB, db);
	v_addc_co_u32_e32 v63, vcc, 0, v49, vcc
	global_store_short v[62:63], v47, off offset:512
	v_mul_f32_e32 v47, v2, v46
	v_add_co_u32_e32 v62, vcc, s7, v48
	v_cvt_pk_bf16_f32 v47, v47, s0
	s_nop 0
	v_addc_co_u32_e32 v63, vcc, 0, v49, vcc
	v_mul_f32_e32 v46, v3, v46
	global_store_short v[62:63], v47, off offset:1024
	v_cvt_pk_bf16_f32 v62, v46, s0
	v_add_co_u32_e32 v46, vcc, s6, v48
	v_lshl_add_u64 v[42:43], v[44:45], 0, v[42:43]
	s_nop 0
	v_addc_co_u32_e32 v47, vcc, 0, v49, vcc
	global_store_short v[46:47], v62, off offset:1536
	v_lshl_add_u64 v[46:47], v[48:49], 0, s[18:19]
	v_lshl_add_u64 v[42:43], v[42:43], 0, v[180:181]
	v_exp_f32_e32 v46, v90
	s_nop 0
	v_mul_f32_e32 v44, v80, v46
	v_cvt_pk_bf16_f32 v44, v44, s0
	global_store_short v[42:43], v44, off offset:512
	v_mul_f32_e32 v44, v81, v46
	v_cvt_pk_bf16_f32 v47, v44, s0
	v_add_co_u32_e32 v44, vcc, s48, v42
	v_mul_f32_e32 v40, v40, v46
	s_nop 0
	v_addc_co_u32_e32 v45, vcc, 0, v43, vcc
	global_store_short v[44:45], v47, off offset:1024
	v_mul_f32_e32 v44, v76, v46
	v_cvt_pk_bf16_f32 v47, v44, s0
	v_add_co_u32_e32 v44, vcc, s7, v42
	v_cvt_pk_bf16_f32 v40, v40, s0
	s_nop 0
	v_addc_co_u32_e32 v45, vcc, 0, v43, vcc
	global_store_short v[44:45], v47, off offset:1536
	v_mul_f32_e32 v44, v77, v46
	v_cvt_pk_bf16_f32 v47, v44, s0
	v_add_co_u32_e32 v44, vcc, s6, v42
	v_mul_f32_e32 v38, v38, v46
	s_nop 0
	v_addc_co_u32_e32 v45, vcc, 0, v43, vcc
	global_store_short v[44:45], v47, off offset:2048
	v_mul_f32_e32 v44, v74, v46
	v_lshl_add_u64 v[42:43], v[42:43], 0, s[16:17]
	v_cvt_pk_bf16_f32 v44, v44, s0
	global_store_short v[42:43], v44, off
	v_mul_f32_e32 v44, v75, v46
	v_cvt_pk_bf16_f32 v47, v44, s0
	v_add_co_u32_e32 v44, vcc, s48, v42
	v_cvt_pk_bf16_f32 v38, v38, s0
	s_nop 0
	v_addc_co_u32_e32 v45, vcc, 0, v43, vcc
	global_store_short v[44:45], v47, off offset:512
	v_mul_f32_e32 v44, v72, v46
	v_cvt_pk_bf16_f32 v47, v44, s0
	v_add_co_u32_e32 v44, vcc, s7, v42
	v_mul_f32_e32 v36, v36, v46
	s_nop 0
	v_addc_co_u32_e32 v45, vcc, 0, v43, vcc
	global_store_short v[44:45], v47, off offset:1024
	v_mul_f32_e32 v44, v73, v46
	v_cvt_pk_bf16_f32 v47, v44, s0
	v_add_co_u32_e32 v44, vcc, s6, v42
	v_cvt_pk_bf16_f32 v36, v36, s0
	s_nop 0
	v_addc_co_u32_e32 v45, vcc, 0, v43, vcc
	global_store_short v[44:45], v47, off offset:1536
	v_mul_f32_e32 v44, v70, v46
	v_lshl_add_u64 v[42:43], v[42:43], 0, s[18:19]
	v_cvt_pk_bf16_f32 v44, v44, s0
	global_store_short v[42:43], v44, off
	v_mul_f32_e32 v44, v71, v46
	v_cvt_pk_bf16_f32 v47, v44, s0
	v_add_co_u32_e32 v44, vcc, s48, v42
	v_mul_f32_e32 v34, v34, v46
	s_nop 0
	v_addc_co_u32_e32 v45, vcc, 0, v43, vcc
	global_store_short v[44:45], v47, off offset:512
	v_mul_f32_e32 v44, v68, v46
	v_cvt_pk_bf16_f32 v47, v44, s0
	v_add_co_u32_e32 v44, vcc, s7, v42
	v_cvt_pk_bf16_f32 v34, v34, s0
	s_nop 0
	v_addc_co_u32_e32 v45, vcc, 0, v43, vcc
	global_store_short v[44:45], v47, off offset:1024
	v_mul_f32_e32 v44, v69, v46
	v_cvt_pk_bf16_f32 v47, v44, s0
	v_add_co_u32_e32 v44, vcc, s6, v42
	v_mul_f32_e32 v32, v32, v46
	s_nop 0
	v_addc_co_u32_e32 v45, vcc, 0, v43, vcc
	global_store_short v[44:45], v47, off offset:1536
	v_mul_f32_e32 v44, v60, v46
	v_lshl_add_u64 v[42:43], v[42:43], 0, s[18:19]
	v_cvt_pk_bf16_f32 v44, v44, s0
	global_store_short v[42:43], v44, off
	v_mul_f32_e32 v44, v61, v46
	v_cvt_pk_bf16_f32 v47, v44, s0
	v_add_co_u32_e32 v44, vcc, s48, v42
	v_cvt_pk_bf16_f32 v32, v32, s0
	s_nop 0
	v_addc_co_u32_e32 v45, vcc, 0, v43, vcc
	global_store_short v[44:45], v47, off offset:512
	v_mul_f32_e32 v44, v58, v46
	v_cvt_pk_bf16_f32 v47, v44, s0
	v_add_co_u32_e32 v44, vcc, s7, v42
	v_mul_f32_e32 v30, v30, v46
	s_nop 0
	v_addc_co_u32_e32 v45, vcc, 0, v43, vcc
	global_store_short v[44:45], v47, off offset:1024
	v_mul_f32_e32 v44, v59, v46
	v_cvt_pk_bf16_f32 v47, v44, s0
	v_add_co_u32_e32 v44, vcc, s6, v42
	v_cvt_pk_bf16_f32 v30, v30, s0
	s_nop 0
	v_addc_co_u32_e32 v45, vcc, 0, v43, vcc
	global_store_short v[44:45], v47, off offset:1536
	v_mul_f32_e32 v44, v56, v46
	v_lshl_add_u64 v[42:43], v[42:43], 0, s[18:19]
	v_cvt_pk_bf16_f32 v44, v44, s0
	global_store_short v[42:43], v44, off
	v_mul_f32_e32 v44, v57, v46
	v_cvt_pk_bf16_f32 v47, v44, s0
	v_add_co_u32_e32 v44, vcc, s48, v42
	v_mul_f32_e32 v28, v28, v46
	s_nop 0
	v_addc_co_u32_e32 v45, vcc, 0, v43, vcc
	global_store_short v[44:45], v47, off offset:512
	v_mul_f32_e32 v44, v54, v46
	v_cvt_pk_bf16_f32 v47, v44, s0
	v_add_co_u32_e32 v44, vcc, s7, v42
	v_cvt_pk_bf16_f32 v28, v28, s0
	s_nop 0
	v_addc_co_u32_e32 v45, vcc, 0, v43, vcc
	global_store_short v[44:45], v47, off offset:1024
	v_mul_f32_e32 v44, v55, v46
	v_cvt_pk_bf16_f32 v47, v44, s0
	v_add_co_u32_e32 v44, vcc, s6, v42
	v_mul_f32_e32 v26, v26, v46
	s_nop 0
	v_addc_co_u32_e32 v45, vcc, 0, v43, vcc
	global_store_short v[44:45], v47, off offset:1536
	v_mul_f32_e32 v44, v52, v46
	v_lshl_add_u64 v[42:43], v[42:43], 0, s[18:19]
	v_cvt_pk_bf16_f32 v44, v44, s0
	global_store_short v[42:43], v44, off
	v_mul_f32_e32 v44, v53, v46
	v_cvt_pk_bf16_f32 v47, v44, s0
	v_add_co_u32_e32 v44, vcc, s48, v42
	v_cvt_pk_bf16_f32 v26, v26, s0
	s_nop 0
	v_addc_co_u32_e32 v45, vcc, 0, v43, vcc
	global_store_short v[44:45], v47, off offset:512
	v_mul_f32_e32 v44, v50, v46
	v_cvt_pk_bf16_f32 v47, v44, s0
	v_add_co_u32_e32 v44, vcc, s7, v42
	v_mul_f32_e32 v24, v24, v46
	s_nop 0
	v_addc_co_u32_e32 v45, vcc, 0, v43, vcc
	global_store_short v[44:45], v47, off offset:1024
	v_mul_f32_e32 v44, v51, v46
	v_cvt_pk_bf16_f32 v47, v44, s0
	v_add_co_u32_e32 v44, vcc, s6, v42
	v_cvt_pk_bf16_f32 v24, v24, s0
	s_nop 0
	v_addc_co_u32_e32 v45, vcc, 0, v43, vcc
	v_lshl_add_u64 v[42:43], v[42:43], 0, s[18:19]
; #define STT(BASE, MUL) { bf16_t* q_ = (BASE) + (size_t)(4 * h) * TOK; _Pragma("unroll") for (int mi = 0; mi < 4; ++mi) _Pragma("unroll") for (int g = 0; g < 4; ++g) { \
;       _Pragma("unroll") for (int e = 0; e < 4; ++e) q_[(size_t)e * TOK] = f2bf(acc[mi][NI][4 * g + e] * (MUL)); q_ += (size_t)8 * TOK; asm volatile("" : "+v"(q_)); } }
; template <int NI> DI void inproj_epi_reg(const Params& p, int layer, int nt, int tok, int h, f32x16 (&acc)[4][2]) {
;     ...
;       STT(KB, db);
	global_store_short v[44:45], v47, off offset:1536
	global_store_short v[42:43], v40, off
	v_mul_f32_e32 v40, v41, v46
	v_cvt_pk_bf16_f32 v44, v40, s0
	v_add_co_u32_e32 v40, vcc, s48, v42
	v_mul_f32_e32 v22, v22, v46
	s_nop 0
	v_addc_co_u32_e32 v41, vcc, 0, v43, vcc
	global_store_short v[40:41], v44, off offset:512
	v_add_co_u32_e32 v40, vcc, s7, v42
	v_cvt_pk_bf16_f32 v22, v22, s0
	s_nop 0
	v_addc_co_u32_e32 v41, vcc, 0, v43, vcc
	global_store_short v[40:41], v38, off offset:1024
	v_mul_f32_e32 v38, v39, v46
	v_cvt_pk_bf16_f32 v40, v38, s0
	v_add_co_u32_e32 v38, vcc, s6, v42
	v_mul_f32_e32 v20, v20, v46
	s_nop 0
	v_addc_co_u32_e32 v39, vcc, 0, v43, vcc
	global_store_short v[38:39], v40, off offset:1536
	v_lshl_add_u64 v[38:39], v[42:43], 0, s[18:19]
	global_store_short v[38:39], v36, off
	v_mul_f32_e32 v36, v37, v46
	v_cvt_pk_bf16_f32 v40, v36, s0
	v_add_co_u32_e32 v36, vcc, s48, v38
	v_cvt_pk_bf16_f32 v20, v20, s0
	s_nop 0
	v_addc_co_u32_e32 v37, vcc, 0, v39, vcc
	global_store_short v[36:37], v40, off offset:512
	v_add_co_u32_e32 v36, vcc, s7, v38
	v_mul_f32_e32 v18, v18, v46
	s_nop 0
	v_addc_co_u32_e32 v37, vcc, 0, v39, vcc
	global_store_short v[36:37], v34, off offset:1024
	v_mul_f32_e32 v34, v35, v46
	v_cvt_pk_bf16_f32 v36, v34, s0
	v_add_co_u32_e32 v34, vcc, s6, v38
	v_cvt_pk_bf16_f32 v18, v18, s0
	s_nop 0
	v_addc_co_u32_e32 v35, vcc, 0, v39, vcc
	global_store_short v[34:35], v36, off offset:1536
	v_lshl_add_u64 v[34:35], v[38:39], 0, s[18:19]
	global_store_short v[34:35], v32, off
	v_mul_f32_e32 v32, v33, v46
	v_cvt_pk_bf16_f32 v36, v32, s0
	v_add_co_u32_e32 v32, vcc, s48, v34
	v_mul_f32_e32 v16, v16, v46
	s_nop 0
	v_addc_co_u32_e32 v33, vcc, 0, v35, vcc
	global_store_short v[32:33], v36, off offset:512
	v_add_co_u32_e32 v32, vcc, s7, v34
	v_cvt_pk_bf16_f32 v16, v16, s0
	s_nop 0
	v_addc_co_u32_e32 v33, vcc, 0, v35, vcc
	global_store_short v[32:33], v30, off offset:1024
	v_mul_f32_e32 v30, v31, v46
	v_cvt_pk_bf16_f32 v32, v30, s0
	v_add_co_u32_e32 v30, vcc, s6, v34
	v_mul_f32_e32 v14, v14, v46
	s_nop 0
	v_addc_co_u32_e32 v31, vcc, 0, v35, vcc
	global_store_short v[30:31], v32, off offset:1536
	v_lshl_add_u64 v[30:31], v[34:35], 0, s[18:19]
	global_store_short v[30:31], v28, off
	v_mul_f32_e32 v28, v29, v46
	v_cvt_pk_bf16_f32 v32, v28, s0
	v_add_co_u32_e32 v28, vcc, s48, v30
	v_cvt_pk_bf16_f32 v14, v14, s0
	s_nop 0
	v_addc_co_u32_e32 v29, vcc, 0, v31, vcc
	global_store_short v[28:29], v32, off offset:512
	v_add_co_u32_e32 v28, vcc, s7, v30
	v_mul_f32_e32 v12, v12, v46
	s_nop 0
	v_addc_co_u32_e32 v29, vcc, 0, v31, vcc
	global_store_short v[28:29], v26, off offset:1024
	v_mul_f32_e32 v26, v27, v46
	v_cvt_pk_bf16_f32 v28, v26, s0
	v_add_co_u32_e32 v26, vcc, s6, v30
	v_cvt_pk_bf16_f32 v12, v12, s0
	s_nop 0
	v_addc_co_u32_e32 v27, vcc, 0, v31, vcc
	global_store_short v[26:27], v28, off offset:1536
	v_lshl_add_u64 v[26:27], v[30:31], 0, s[18:19]
	global_store_short v[26:27], v24, off
	v_mul_f32_e32 v24, v25, v46
	v_cvt_pk_bf16_f32 v28, v24, s0
	v_add_co_u32_e32 v24, vcc, s48, v26
	v_mul_f32_e32 v10, v10, v46
	s_nop 0
	v_addc_co_u32_e32 v25, vcc, 0, v27, vcc
	global_store_short v[24:25], v28, off offset:512
	v_add_co_u32_e32 v24, vcc, s7, v26
	v_cvt_pk_bf16_f32 v10, v10, s0
	s_nop 0
	v_addc_co_u32_e32 v25, vcc, 0, v27, vcc
	global_store_short v[24:25], v22, off offset:1024
	v_mul_f32_e32 v22, v23, v46
	v_cvt_pk_bf16_f32 v24, v22, s0
	v_add_co_u32_e32 v22, vcc, s6, v26
	v_mul_f32_e32 v8, v8, v46
	s_nop 0
	v_addc_co_u32_e32 v23, vcc, 0, v27, vcc
	global_store_short v[22:23], v24, off offset:1536
	v_lshl_add_u64 v[22:23], v[26:27], 0, s[18:19]
	global_store_short v[22:23], v20, off
	v_mul_f32_e32 v20, v21, v46
	v_cvt_pk_bf16_f32 v24, v20, s0
	v_add_co_u32_e32 v20, vcc, s48, v22
	v_cvt_pk_bf16_f32 v8, v8, s0
	s_nop 0
	v_addc_co_u32_e32 v21, vcc, 0, v23, vcc
	global_store_short v[20:21], v24, off offset:512
	v_add_co_u32_e32 v20, vcc, s7, v22
	v_mul_f32_e32 v6, v6, v46
	s_nop 0
	v_addc_co_u32_e32 v21, vcc, 0, v23, vcc
	global_store_short v[20:21], v18, off offset:1024
	v_mul_f32_e32 v18, v19, v46
	v_cvt_pk_bf16_f32 v20, v18, s0
	v_add_co_u32_e32 v18, vcc, s6, v22
	v_cvt_pk_bf16_f32 v6, v6, s0
	s_nop 0
	v_addc_co_u32_e32 v19, vcc, 0, v23, vcc
	global_store_short v[18:19], v20, off offset:1536
	v_lshl_add_u64 v[18:19], v[22:23], 0, s[18:19]
	global_store_short v[18:19], v16, off
	v_mul_f32_e32 v16, v17, v46
	v_cvt_pk_bf16_f32 v20, v16, s0
	v_add_co_u32_e32 v16, vcc, s48, v18
	v_mul_f32_e32 v4, v4, v46
	s_nop 0
	v_addc_co_u32_e32 v17, vcc, 0, v19, vcc
	global_store_short v[16:17], v20, off offset:512
	v_add_co_u32_e32 v16, vcc, s7, v18
	v_cvt_pk_bf16_f32 v4, v4, s0
	s_nop 0
	v_addc_co_u32_e32 v17, vcc, 0, v19, vcc
	global_store_short v[16:17], v14, off offset:1024
	v_mul_f32_e32 v14, v15, v46
	v_cvt_pk_bf16_f32 v16, v14, s0
	v_add_co_u32_e32 v14, vcc, s6, v18
	v_mul_f32_e32 v2, v2, v46
	s_nop 0
	v_addc_co_u32_e32 v15, vcc, 0, v19, vcc
	global_store_short v[14:15], v16, off offset:1536
	v_lshl_add_u64 v[14:15], v[18:19], 0, s[18:19]
	global_store_short v[14:15], v12, off
	v_mul_f32_e32 v12, v13, v46
	v_cvt_pk_bf16_f32 v16, v12, s0
	v_add_co_u32_e32 v12, vcc, s48, v14
	v_cvt_pk_bf16_f32 v2, v2, s0
	s_nop 0
	v_addc_co_u32_e32 v13, vcc, 0, v15, vcc
	global_store_short v[12:13], v16, off offset:512
	v_add_co_u32_e32 v12, vcc, s7, v14
	s_nop 1
	v_addc_co_u32_e32 v13, vcc, 0, v15, vcc
	global_store_short v[12:13], v10, off offset:1024
	v_mul_f32_e32 v10, v11, v46
	v_cvt_pk_bf16_f32 v12, v10, s0
	v_add_co_u32_e32 v10, vcc, s6, v14
	s_nop 1
	v_addc_co_u32_e32 v11, vcc, 0, v15, vcc
	global_store_short v[10:11], v12, off offset:1536
	v_lshl_add_u64 v[10:11], v[14:15], 0, s[18:19]
	global_store_short v[10:11], v8, off
	v_mul_f32_e32 v8, v9, v46
	v_cvt_pk_bf16_f32 v12, v8, s0
	v_add_co_u32_e32 v8, vcc, s48, v10
	s_nop 1
	v_addc_co_u32_e32 v9, vcc, 0, v11, vcc
	global_store_short v[8:9], v12, off offset:512
	v_add_co_u32_e32 v8, vcc, s7, v10
	s_nop 1
	v_addc_co_u32_e32 v9, vcc, 0, v11, vcc
	global_store_short v[8:9], v6, off offset:1024
	v_mul_f32_e32 v6, v7, v46
	v_cvt_pk_bf16_f32 v8, v6, s0
	v_add_co_u32_e32 v6, vcc, s6, v10
	s_nop 1
	v_addc_co_u32_e32 v7, vcc, 0, v11, vcc
	global_store_short v[6:7], v8, off offset:1536
	v_lshl_add_u64 v[6:7], v[10:11], 0, s[18:19]
	global_store_short v[6:7], v4, off
	v_mul_f32_e32 v4, v5, v46
	v_cvt_pk_bf16_f32 v8, v4, s0
	v_add_co_u32_e32 v4, vcc, 0x4000, v6
	s_nop 1
	v_addc_co_u32_e32 v5, vcc, 0, v7, vcc
	global_store_short v[4:5], v8, off offset:512
	v_add_co_u32_e32 v4, vcc, 0x8000, v6
	s_nop 1
	v_addc_co_u32_e32 v5, vcc, 0, v7, vcc
	global_store_short v[4:5], v2, off offset:1024
	v_mul_f32_e32 v2, v3, v46
	v_cvt_pk_bf16_f32 v4, v2, s0
	v_add_co_u32_e32 v2, vcc, 0xc000, v6
	s_nop 1
	v_addc_co_u32_e32 v3, vcc, 0, v7, vcc
	global_store_short v[2:3], v4, off offset:1536
	v_lshl_add_u64 v[2:3], v[6:7], 0, s[18:19]
